# RG-LRU carry pass: gate biases / softplus terms also resident in VGPRs (per-block constants), no loads inside the gate sections
# speedup vs baseline: 1.0779x; 1.0005x over previous
; template <bool FINAL>
; __device__ void phase_lru(const Params& p, int l, unsigned char* smem) {
;     ...
;   const int tid = TIDX(), lane = tid & 63, w = tid >> 6, l15 = lane & 15, g = lane >> 4;
;   const int e_ = tid & 63, qd = tid >> 6;
;   const int NIT = NCHUNK * 8;
;   const int step = gridDim.x;
;   int it = BIDX();
;   uint4 x0 = make_uint4(0, 0, 0, 0), x1 = x0, x2 = x0;
;   auto load_x = [&](int item, uint4& a0, uint4& a1, uint4& a2) {
;     const int ci = item >> 3, nb = item & 7;
;     const int tb = ci * 64, pos0 = tok_pos(tb), S = tok_len(tb);
;     const u16* zb = p.Z + (long)(tb - 2) * DIN + C_LX + nb * 64;
;     { int idx = tid, r = idx >> 3, ch = idx & 7, pp = pos0 - 2 + r;
;       a0 = (pp >= 0 && pp < S) ? *(const uint4*)(zb + (long)r * DIN + ch * 8) : make_uint4(0, 0, 0, 0); }
;     { int idx = tid + 256, r = idx >> 3, ch = idx & 7, pp = pos0 - 2 + r;
;       a1 = (pp >= 0 && pp < S) ? *(const uint4*)(zb + (long)r * DIN + ch * 8) : make_uint4(0, 0, 0, 0); }
;     { int idx = tid + 512, r = idx >> 3, ch = idx & 7, pp = pos0 - 2 + r;
;       a2 = (idx < 67 * 8 && pp >= 0 && pp < S) ? *(const uint4*)(zb + (long)r * DIN + ch * 8) : make_uint4(0, 0, 0, 0); }
;   };
;   if (it < NIT) load_x(it, x0, x1, x2);
;     ...
;         uf[0] = *(const bf16x8*)(ub + (16 * w + l15) * 72 + g * 8);
;         uf[1] = *(const bf16x8*)(ub + (16 * w + l15) * 72 + 32 + g * 8);
;         const int t = 16 * w + l15;
; #pragma unroll
;         for (int et = 0; et < 4; ++et) {
;           f32x4 ar = {0.f, 0.f, 0.f, 0.f}, ai = {0.f, 0.f, 0.f, 0.f};
;           const u16* wr = p.WLRU + ((((size_t)(l * 2 + d) * 2 + 0) * 8 + nb) * 64 + et * 16 + l15) * 64 + g * 8;
;           const u16* wi = p.WLRU + ((((size_t)(l * 2 + d) * 2 + 1) * 8 + nb) * 64 + et * 16 + l15) * 64 + g * 8;
; #pragma unroll
;           for (int ks = 0; ks < 2; ++ks) {
;             ar = mfma16(*(const bf16x8*)(wr + ks * 32), uf[ks], ar);
;             ai = mfma16(*(const bf16x8*)(wi + ks * 32), uf[ks], ai);
;           }
;           const int e0 = et * 16 + 4 * g, ch0 = nb * 64 + e0;
;           const float4 ba4 = *(const float4*)(p.ba + (l * 2 + d) * 512 + ch0);
;           const float4 bx4 = *(const float4*)(p.bx + (l * 2 + d) * 512 + ch0);
;           const float4 sp4 = *(const float4*)(p.SP8 + (l * 2 + d) * 512 + ch0);
;           const float4 uu = *(const float4*)(u32 + t * 64 + e0);
.LBB0_373:
	s_or_b64 exec, exec, s[40:41]
	v_and_b32_e32 v59, 63, v45
	v_and_b32_e32 v12, 0x7fffffc0, v12
	v_ashrrev_i32_e32 v13, 6, v45
	v_lshlrev_b32_e32 v16, 1, v59
	v_lshlrev_b32_e32 v12, 1, v12
	v_lshlrev_b32_e32 v18, 1, v144
	v_and_b32_e32 v60, 15, v45
	v_add_u32_e32 v17, 0, v16
	v_add3_u32 v61, 0, v12, v18
	v_lshlrev_b32_e32 v18, 4, v13
	v_add_u32_e32 v62, v17, v16
	v_or_b32_e32 v16, v18, v60
	v_mul_lo_u32 v19, v16, s28
	v_and_b32_e32 v20, 48, v45
	v_bfe_u32 v14, v45, 4, 2
	v_add3_u32 v46, 0, v19, v20
	v_and_b32_e32 v19, 0x3fffffc0, v45
	s_lshl_b32 s36, s72, 6
	s_and_b32 s30, 0xffff, s42
	v_lshlrev_b32_e32 v44, 3, v14
	v_lshlrev_b32_e32 v63, 2, v14
	v_lshlrev_b32_e32 v14, 2, v45
	v_readlane_b32 s4, v248, 16
	v_lshlrev_b32_e32 v19, 2, v19
	v_lshlrev_b32_e32 v20, 2, v59
	s_cmp_lg_u32 s30, 0
	v_add_u32_e32 v64, s4, v14
	v_add3_u32 v65, s4, v19, v20
	s_movk_i32 s4, 0x70
	s_cselect_b64 s[42:43], -1, 0
	v_mad_u64_u32 v[48:49], s[46:47], v16, s4, v[46:47]
	v_readlane_b32 s4, v248, 17
	s_cmp_lg_u64 s[42:43], 0
	v_mad_i64_i32 v[40:41], s[30:31], v47, s26, 0
	v_mad_i64_i32 v[42:43], s[30:31], v57, s26, 0
	v_add_u32_e32 v97, s4, v14
	v_readlane_b32 s4, v248, 18
	s_addc_u32 s62, s58, 0
	s_lshl_b32 s30, s22, 1
	v_add_u32_e32 v98, s4, v14
	v_readlane_b32 s4, v248, 19
	s_or_b32 s50, s30, 1
	s_ashr_i32 s31, s30, 31
	v_add_u32_e32 v99, s4, v14
	v_readlane_b32 s4, v248, 20
	s_lshl_b32 s44, s22, 10
	s_lshl_b32 s52, s50, 9
	v_add_u32_e32 v100, s4, v14
	v_readlane_b32 s4, v250, 5
	s_lshl_b32 s63, s22, 11
	s_lshl_b32 s64, s22, 9
	s_ashr_i32 s45, s44, 31
	s_ashr_i32 s51, s50, 31
	s_ashr_i32 s53, s52, 31
	s_lshl_b64 s[30:31], s[30:31], 17
	v_readlane_b32 s10, v250, 11
	v_or_b32_e32 v18, 1, v18
	v_readlane_b32 s11, v250, 12
	v_readlane_b32 s16, v250, 17
	v_readlane_b32 s17, v250, 18
	v_readlane_b32 s18, v250, 19
	v_readlane_b32 s19, v250, 20
	s_add_u32 s94, s10, s30
	v_lshlrev_b32_e32 v12, 11, v13
	v_lshlrev_b32_e32 v66, 12, v13
	v_mul_lo_u32 v13, v13, s27
	v_lshlrev_b32_e32 v67, 8, v18
	v_mul_lo_u32 v18, v18, s28
	s_mov_b32 s98, s22
	s_addc_u32 s95, s11, s31
	v_readlane_b32 s16, v250, 37
	s_lshl_b64 s[48:49], s[44:45], 2
	v_readlane_b32 s24, v250, 45
	v_readlane_b32 s25, v250, 46
	s_add_u32 s44, s24, s48
	v_readlane_b32 s28, v250, 49
	s_addc_u32 s45, s25, s49
	v_or_b32_e32 v16, v66, v20
	v_readlane_b32 s29, v250, 50
	s_add_u32 s46, s28, s48
	v_or_b32_e32 v68, 0x200, v66
	v_add_u32_e32 v49, 0, v16
	v_or_b32_e32 v16, v67, v20
	v_readlane_b32 s14, v250, 15
	s_addc_u32 s47, s29, s49
	v_or_b32_e32 v69, 0x300, v66
	v_add_u32_e32 v82, 0, v16
	v_or_b32_e32 v16, v68, v20
	v_readlane_b32 s15, v250, 16
	s_add_u32 s48, s14, s48
	v_or_b32_e32 v70, 0x400, v66
	v_add_u32_e32 v83, 0, v16
	v_or_b32_e32 v16, v69, v20
	s_addc_u32 s49, s15, s49
	s_lshl_b64 s[50:51], s[50:51], 17
	v_or_b32_e32 v71, 0x500, v66
	v_add_u32_e32 v84, 0, v16
	v_or_b32_e32 v16, v70, v20
	s_add_u32 s50, s10, s50
	v_or_b32_e32 v72, 0x600, v66
	v_add_u32_e32 v85, 0, v16
	v_or_b32_e32 v16, v71, v20
	s_addc_u32 s51, s11, s51
	s_lshl_b64 s[56:57], s[52:53], 2
	v_or_b32_e32 v73, 0x700, v66
	v_add_u32_e32 v86, 0, v16
	v_or_b32_e32 v16, v72, v20
	s_add_u32 s52, s24, s56
	v_or_b32_e32 v74, 0x800, v66
	v_add_u32_e32 v87, 0, v16
	v_or_b32_e32 v16, v73, v20
	s_addc_u32 s53, s25, s57
	v_or_b32_e32 v75, 0x900, v66
	v_add_u32_e32 v88, 0, v16
	v_or_b32_e32 v16, v74, v20
	s_add_u32 s54, s28, s56
	v_or_b32_e32 v76, 0xa00, v66
	v_add_u32_e32 v89, 0, v16
	v_or_b32_e32 v16, v75, v20
	s_addc_u32 s55, s29, s57
	v_or_b32_e32 v77, 0xb00, v66
	v_add_u32_e32 v90, 0, v16
	v_or_b32_e32 v16, v76, v20
	s_add_u32 s56, s14, s56
	v_or_b32_e32 v78, 0xc00, v66
	v_add_u32_e32 v91, 0, v16
	v_or_b32_e32 v16, v77, v20
	s_addc_u32 s57, s15, s57
	s_lshl_b32 s65, s62, 6
	v_or_b32_e32 v79, 0xd00, v66
	v_add_u32_e32 v92, 0, v16
	v_or_b32_e32 v16, v78, v20
	s_cmp_lg_u64 s[42:43], 0
	v_cndmask_b32_e64 v15, 0, 1, s[42:43]
	v_or_b32_e32 v80, 0xe00, v66
	v_add_u32_e32 v93, 0, v16
	v_or_b32_e32 v16, v79, v20
	s_addc_u32 s42, s72, s58
	v_or_b32_e32 v81, 0xf00, v66
	v_add_u32_e32 v94, 0, v16
	v_or_b32_e32 v16, v80, v20
	s_lshl_b32 s66, s42, 3
	v_readfirstlane_b32 s42, v15
	v_add_u32_e32 v95, 0, v16
	v_or_b32_e32 v16, v81, v20
	s_lshl_b32 s68, s58, 6
	s_lshl_b32 s42, s42, 6
	v_cmp_gt_u32_e64 s[40:41], 64, v45
	v_add_u32_e32 v96, 0, v16
	s_lshl_b32 s67, s62, 3
	s_add_i32 s68, s68, s42
	v_add_u32_e32 v101, v17, v12
	v_add_u32_e32 v102, v17, v13
	v_add_u32_e32 v103, v17, v18
	v_readlane_b32 s5, v250, 6
	v_readlane_b32 s6, v250, 7
	v_readlane_b32 s7, v250, 8
	v_readlane_b32 s8, v250, 9
	v_readlane_b32 s9, v250, 10
	v_readlane_b32 s12, v250, 13
	v_readlane_b32 s13, v250, 14
	v_readlane_b32 s17, v250, 38
	v_readlane_b32 s18, v250, 39
	v_readlane_b32 s19, v250, 40
	v_readlane_b32 s20, v250, 41
	v_readlane_b32 s21, v250, 42
	v_readlane_b32 s22, v250, 43
	v_readlane_b32 s23, v250, 44
	v_readlane_b32 s26, v250, 47
	v_readlane_b32 s27, v250, 48
	v_readlane_b32 s30, v250, 51
	v_readlane_b32 s31, v250, 52
	s_and_b32 s32, s36, 0x1c0
	v_lshrrev_b32_e32 v12, 6, v147
	v_and_b32_e32 v22, 15, v147
	v_lshlrev_b32_e32 v13, 4, v12
	v_or_b32_e32 v13, v13, v22
	v_or_b32_e32 v13, s32, v13
	v_lshlrev_b32_e32 v14, 7, v13
	v_mov_b32_e32 v15, v145
	v_bfe_u32 v16, v147, 4, 2
	v_lshlrev_b32_e32 v17, 4, v16
	v_add_u32_e32 v14, v14, v17
	v_lshl_add_u64 v[18:19], s[94:95], 0, v[14:15]
	global_load_dwordx4 v[180:183], v[18:19], off
	global_load_dwordx4 v[184:187], v[18:19], off offset:64
	v_add_co_u32_e32 v20, vcc, 0x10000, v18
	s_nop 0
	v_addc_co_u32_e32 v21, vcc, 0, v19, vcc
	global_load_dwordx4 v[188:191], v[20:21], off
	global_load_dwordx4 v[192:195], v[20:21], off offset:64
	v_lshl_add_u64 v[18:19], s[50:51], 0, v[14:15]
	global_load_dwordx4 v[232:235], v[18:19], off
	global_load_dwordx4 v[236:239], v[18:19], off offset:64
	v_add_co_u32_e32 v20, vcc, 0x10000, v18
	s_nop 0
	v_addc_co_u32_e32 v21, vcc, 0, v19, vcc
	global_load_dwordx4 v[240:243], v[20:21], off
	global_load_dwordx4 v[244:247], v[20:21], off offset:64
	v_mul_u32_u24_e32 v229, 0x90, v22
	v_add_u32_e32 v229, v229, v17
	v_lshlrev_b32_e32 v230, 8, v22
	v_add_u32_e32 v230, v230, v17
	v_lshl_add_u32 v230, v12, 6, v230
	v_lshlrev_b32_e32 v231, 4, v12
	v_lshl_add_u32 v231, v16, 2, v231
	v_or_b32_e32 v231, s32, v231
	v_lshlrev_b32_e32 v231, 2, v231
	global_load_dwordx4 v[122:125], v231, s[44:45]
	global_load_dwordx4 v[126:129], v231, s[46:47]
	global_load_dwordx4 v[130:133], v231, s[48:49]
	global_load_dwordx4 v[134:137], v231, s[52:53]
	global_load_dwordx4 v[138:141], v231, s[54:55]
	global_load_dwordx4 v[150:153], v231, s[56:57]
	s_branch .LBB0_375

; __device__ __forceinline__ float bf2f(unsigned h) { return __uint_as_float(h << 16); }
; template <bool FINAL>
; __device__ void phase_lru(const Params& p, int l, unsigned char* smem) {
;     ...
;     {
;       const int ch = nb * 64 + e_;
;       const float cw0 = p.conv_w[(l * 4 + 0) * 512 + ch], cw1 = p.conv_w[(l * 4 + 1) * 512 + ch],
;                   cw2 = p.conv_w[(l * 4 + 2) * 512 + ch], cw3 = p.conv_w[(l * 4 + 3) * 512 + ch];
;       const float cb = p.conv_b[l * 512 + ch];
;       float xv[19];
; #pragma unroll
;       for (int k = 0; k < 19; ++k) xv[k] = bf2f(xs[(qd * 16 + k) * 64 + e_]);
; #pragma unroll
;       for (int tt = 0; tt < 16; ++tt) {
;         const int t = qd * 16 + tt;
;         const float u = cb + xv[tt] * cw0 + xv[tt + 1] * cw1 + xv[tt + 2] * cw2 + xv[tt + 3] * cw3;
;         u32[t * 64 + e_] = u;
;         ub[t * 72 + e_] = (u16)f2bf(u);
;       }
;     }
.LBB0_385:
	s_and_b32 s60, s36, 0x1c0
	v_or_b32_e32 v18, s60, v59
	v_or_b32_e32 v12, s63, v18
	v_readlane_b32 s4, v250, 37
	v_ashrrev_i32_e32 v13, 31, v12
	v_readlane_b32 s6, v250, 39
	v_readlane_b32 s7, v250, 40
	v_readlane_b32 s8, v250, 41
	v_readlane_b32 s9, v250, 42
	v_lshl_add_u64 v[14:15], v[12:13], 2, s[6:7]
	v_add_co_u32_e32 v16, vcc, 0x1000, v14
	global_load_dword v13, v[14:15], off
	global_load_dword v12, v[14:15], off offset:2048
	v_addc_co_u32_e32 v17, vcc, 0, v15, vcc
	global_load_dword v15, v[16:17], off
	global_load_dword v14, v[16:17], off offset:2048
	v_or_b32_e32 v16, s64, v18
	v_ashrrev_i32_e32 v17, 31, v16
	v_lshl_add_u64 v[16:17], v[16:17], 2, s[8:9]
	global_load_dword v16, v[16:17], off
	ds_read_u16 v17, v101
	ds_read_u16 v18, v101 offset:128
	ds_read_u16 v19, v101 offset:256
	ds_read_u16 v20, v101 offset:384
	ds_read_u16 v21, v101 offset:512
	ds_read_u16 v22, v101 offset:640
	ds_read_u16 v23, v101 offset:768
	ds_read_u16 v24, v101 offset:896
	s_waitcnt lgkmcnt(7)
	v_lshlrev_b32_e32 v17, 16, v17
	s_waitcnt lgkmcnt(6)
	v_lshlrev_b32_e32 v18, 16, v18
	s_waitcnt lgkmcnt(5)
	v_lshlrev_b32_e32 v19, 16, v19
	s_waitcnt lgkmcnt(4)
	v_lshlrev_b32_e32 v20, 16, v20
	v_add_u32_e32 v50, v62, v66
	ds_read_u16 v25, v101 offset:1024
	ds_read_u16 v26, v101 offset:1152
	ds_read_u16 v27, v101 offset:1280
	ds_read_u16 v28, v101 offset:1408
	ds_read_u16 v29, v101 offset:1536
	ds_read_u16 v30, v101 offset:1664
	ds_read_u16 v31, v101 offset:1792
	ds_read_u16 v32, v101 offset:1920
	ds_read_u16 v33, v101 offset:2048
	ds_read_u16 v34, v101 offset:2176
	ds_read_u16 v35, v101 offset:2304
	s_waitcnt lgkmcnt(14)
	v_lshlrev_b32_e32 v21, 16, v21
	s_waitcnt lgkmcnt(13)
	v_lshlrev_b32_e32 v22, 16, v22
	s_waitcnt lgkmcnt(12)
	v_lshlrev_b32_e32 v23, 16, v23
	s_waitcnt lgkmcnt(11)
	v_lshlrev_b32_e32 v24, 16, v24
	s_waitcnt lgkmcnt(10)
	v_lshlrev_b32_e32 v25, 16, v25
	s_waitcnt lgkmcnt(9)
	v_lshlrev_b32_e32 v26, 16, v26
	s_waitcnt lgkmcnt(8)
	v_lshlrev_b32_e32 v27, 16, v27
	s_waitcnt lgkmcnt(7)
	v_lshlrev_b32_e32 v28, 16, v28
	s_waitcnt lgkmcnt(6)
	v_lshlrev_b32_e32 v29, 16, v29
	s_waitcnt lgkmcnt(5)
	v_lshlrev_b32_e32 v30, 16, v30
	s_waitcnt lgkmcnt(4)
	v_lshlrev_b32_e32 v31, 16, v31
	s_waitcnt lgkmcnt(3)
	v_lshlrev_b32_e32 v32, 16, v32
	s_waitcnt lgkmcnt(2)
	v_lshlrev_b32_e32 v33, 16, v33
	s_ashr_i32 s42, s72, 3
	s_ashr_i32 s43, s42, 31
	s_waitcnt lgkmcnt(1)
	v_lshlrev_b32_e32 v34, 16, v34
	s_lshl_b64 s[42:43], s[42:43], 10
	v_add_u32_e32 v144, s60, v45
	s_waitcnt lgkmcnt(0)
	v_lshlrev_b32_e32 v35, 16, v35
	v_lshlrev_b32_e32 v54, 1, v44
	v_mov_b32_e32 v55, v145
	v_readlane_b32 s5, v250, 38
	s_mov_b64 s[4:5], 0x10000
	v_or_b32_e32 v56, s60, v63
	v_lshlrev_b32_e32 v104, 2, v56
	s_mov_b32 s6, 0xbe800000
	s_mov_b64 s[8:9], 0x10800
	v_readlane_b32 s10, v250, 43
	v_readlane_b32 s11, v250, 44
	v_readlane_b32 s12, v250, 45
	v_readlane_b32 s13, v250, 46
	v_readlane_b32 s14, v250, 47
	v_readlane_b32 s15, v250, 48
	v_readlane_b32 s16, v250, 49
	v_readlane_b32 s17, v250, 50
	v_readlane_b32 s18, v250, 51
	v_readlane_b32 s19, v250, 52
	s_waitcnt vmcnt(0)
	v_fma_f32 v17, v13, v17, v16
	v_fmac_f32_e32 v17, v12, v18
	v_fmac_f32_e32 v17, v15, v19
	v_fmac_f32_e32 v17, v14, v20
	ds_write_b32 v50, v17 offset:8704
	v_cvt_pk_bf16_f32 v17, v17, s0
	ds_write_b16 v102, v17 offset:25088
	v_fma_f32 v17, v13, v18, v16
	v_fmac_f32_e32 v17, v12, v19
	v_fmac_f32_e32 v17, v15, v20
	v_fmac_f32_e32 v17, v14, v21
	v_add_u32_e32 v18, v62, v67
	ds_write_b32 v18, v17 offset:8704
	v_cvt_pk_bf16_f32 v17, v17, s0
	ds_write_b16 v103, v17 offset:25088
	v_fma_f32 v17, v13, v19, v16
	v_fmac_f32_e32 v17, v12, v20
	v_fmac_f32_e32 v17, v15, v21
	v_fmac_f32_e32 v17, v14, v22
	v_add_u32_e32 v18, v62, v68
	ds_write_b32 v18, v17 offset:8704
	v_cvt_pk_bf16_f32 v17, v17, s0
	ds_write_b16 v103, v17 offset:25232
	v_fma_f32 v17, v13, v20, v16
	v_fmac_f32_e32 v17, v12, v21
	v_fmac_f32_e32 v17, v15, v22
	v_fmac_f32_e32 v17, v14, v23
	v_add_u32_e32 v18, v62, v69
	ds_write_b32 v18, v17 offset:8704
	v_cvt_pk_bf16_f32 v17, v17, s0
	ds_write_b16 v103, v17 offset:25376
	v_fma_f32 v17, v13, v21, v16
	v_fmac_f32_e32 v17, v12, v22
	v_fmac_f32_e32 v17, v15, v23
	v_fmac_f32_e32 v17, v14, v24
	v_add_u32_e32 v18, v62, v70
	ds_write_b32 v18, v17 offset:8704
	v_cvt_pk_bf16_f32 v17, v17, s0
	ds_write_b16 v103, v17 offset:25520
	v_fma_f32 v17, v13, v22, v16
	v_fmac_f32_e32 v17, v12, v23
	v_fmac_f32_e32 v17, v15, v24
	v_fmac_f32_e32 v17, v14, v25
	v_add_u32_e32 v18, v62, v71
	ds_write_b32 v18, v17 offset:8704
	v_cvt_pk_bf16_f32 v17, v17, s0
	ds_write_b16 v103, v17 offset:25664
	v_fma_f32 v17, v13, v23, v16
	v_fmac_f32_e32 v17, v12, v24
	v_fmac_f32_e32 v17, v15, v25
	v_fmac_f32_e32 v17, v14, v26
	v_add_u32_e32 v18, v62, v72
	ds_write_b32 v18, v17 offset:8704
	v_cvt_pk_bf16_f32 v17, v17, s0
	ds_write_b16 v103, v17 offset:25808
	v_fma_f32 v17, v13, v24, v16
	v_fmac_f32_e32 v17, v12, v25
	v_fmac_f32_e32 v17, v15, v26
	v_fmac_f32_e32 v17, v14, v27
	v_add_u32_e32 v18, v62, v73
	ds_write_b32 v18, v17 offset:8704
	v_cvt_pk_bf16_f32 v17, v17, s0
	ds_write_b16 v103, v17 offset:25952
	v_fma_f32 v17, v13, v25, v16
	v_fmac_f32_e32 v17, v12, v26
	v_fmac_f32_e32 v17, v15, v27
	v_fmac_f32_e32 v17, v14, v28
	v_add_u32_e32 v18, v62, v74
	ds_write_b32 v18, v17 offset:8704
	v_cvt_pk_bf16_f32 v17, v17, s0
	ds_write_b16 v103, v17 offset:26096
	v_fma_f32 v17, v13, v26, v16
	v_fmac_f32_e32 v17, v12, v27
	v_fmac_f32_e32 v17, v15, v28
	v_fmac_f32_e32 v17, v14, v29
	v_add_u32_e32 v18, v62, v75
	ds_write_b32 v18, v17 offset:8704
	v_cvt_pk_bf16_f32 v17, v17, s0
	ds_write_b16 v103, v17 offset:26240
	v_fma_f32 v17, v13, v27, v16
	v_fmac_f32_e32 v17, v12, v28
; template <bool FINAL>
; __device__ void phase_lru(const Params& p, int l, unsigned char* smem) {
;     ...
;       for (int tt = 0; tt < 16; ++tt) {
;         const int t = qd * 16 + tt;
;         const float u = cb + xv[tt] * cw0 + xv[tt + 1] * cw1 + xv[tt + 2] * cw2 + xv[tt + 3] * cw3;
;         u32[t * 64 + e_] = u;
;         ub[t * 72 + e_] = (u16)f2bf(u);
;       }
;     }
;     ...
;       {
;         bf16x8 uf[2];
;         uf[0] = *(const bf16x8*)(ub + (16 * w + l15) * 72 + g * 8);
;         uf[1] = *(const bf16x8*)(ub + (16 * w + l15) * 72 + 32 + g * 8);
;         const int t = 16 * w + l15;
; #pragma unroll
;         for (int et = 0; et < 4; ++et) {
;           f32x4 ar = {0.f, 0.f, 0.f, 0.f}, ai = {0.f, 0.f, 0.f, 0.f};
;           const u16* wr = p.WLRU + ((((size_t)(l * 2 + d) * 2 + 0) * 8 + nb) * 64 + et * 16 + l15) * 64 + g * 8;
;           const u16* wi = p.WLRU + ((((size_t)(l * 2 + d) * 2 + 1) * 8 + nb) * 64 + et * 16 + l15) * 64 + g * 8;
; #pragma unroll
;           for (int ks = 0; ks < 2; ++ks) {
;             ar = mfma16(*(const bf16x8*)(wr + ks * 32), uf[ks], ar);
;             ai = mfma16(*(const bf16x8*)(wi + ks * 32), uf[ks], ai);
;           }
;           const int e0 = et * 16 + 4 * g, ch0 = nb * 64 + e0;
;           const float4 ba4 = *(const float4*)(p.ba + (l * 2 + d) * 512 + ch0);
;           const float4 bx4 = *(const float4*)(p.bx + (l * 2 + d) * 512 + ch0);
;           const float4 sp4 = *(const float4*)(p.SP8 + (l * 2 + d) * 512 + ch0);
;           const float4 uu = *(const float4*)(u32 + t * 64 + e0);
;           const float* bap = (const float*)&ba4; const float* bxp = (const float*)&bx4;
;           const float* spp = (const float*)&sp4; const float* uup = (const float*)&uu;
;           f32x4 av, bv;
; #pragma unroll
;           for (int j = 0; j < 4; ++j) {
;             float r = sigmoidf_(ar[j] + bap[j]);
;             float ig = sigmoidf_(ai[j] + bxp[j]);
;             float la = spp[j] * r;
;             float av_ = __expf(la);
;             float t2 = 2.0f * la;
;             float ser = -t2 * (1.f + t2 * 0.5f * (1.f + t2 * (1.f / 3.f) * (1.f + t2 * 0.25f * (1.f + t2 * 0.2f))));
;             float om = (t2 > -0.25f) ? ser : (1.0f - av_ * av_);
;             av[j] = av_;
;             bv[j] = __builtin_amdgcn_sqrtf(om) * ig * uup[j];
;           }
;           *(f32x4*)(sa + t * 64 + e0) = av;
	v_fmac_f32_e32 v17, v15, v29
	v_fmac_f32_e32 v17, v14, v30
	v_add_u32_e32 v18, v62, v76
	ds_write_b32 v18, v17 offset:8704
	v_cvt_pk_bf16_f32 v17, v17, s0
	ds_write_b16 v103, v17 offset:26384
	v_fma_f32 v17, v13, v28, v16
	v_fmac_f32_e32 v17, v12, v29
	v_fmac_f32_e32 v17, v15, v30
	v_fmac_f32_e32 v17, v14, v31
	v_add_u32_e32 v18, v62, v77
	ds_write_b32 v18, v17 offset:8704
	v_cvt_pk_bf16_f32 v17, v17, s0
	ds_write_b16 v103, v17 offset:26528
	v_fma_f32 v17, v13, v29, v16
	v_fmac_f32_e32 v17, v12, v30
	v_fmac_f32_e32 v17, v15, v31
	v_fmac_f32_e32 v17, v14, v32
	v_add_u32_e32 v18, v62, v78
	ds_write_b32 v18, v17 offset:8704
	v_cvt_pk_bf16_f32 v17, v17, s0
	ds_write_b16 v103, v17 offset:26672
	v_fma_f32 v17, v13, v30, v16
	v_fmac_f32_e32 v17, v12, v31
	v_fmac_f32_e32 v17, v15, v32
	v_fmac_f32_e32 v17, v14, v33
	v_add_u32_e32 v18, v62, v79
	ds_write_b32 v18, v17 offset:8704
	v_cvt_pk_bf16_f32 v17, v17, s0
	ds_write_b16 v103, v17 offset:26816
	v_fma_f32 v17, v13, v31, v16
	v_fmac_f32_e32 v16, v13, v32
	v_fmac_f32_e32 v17, v12, v32
	v_fmac_f32_e32 v16, v12, v33
	v_or_b32_e32 v20, s60, v60
	v_fmac_f32_e32 v17, v15, v33
	v_fmac_f32_e32 v16, v15, v34
	v_lshl_add_u64 v[50:51], v[144:145], 0, s[42:43]
	v_lshlrev_b32_e32 v144, 7, v20
	v_fmac_f32_e32 v17, v14, v34
	v_add_u32_e32 v18, v62, v80
	v_fmac_f32_e32 v16, v14, v35
	v_add_u32_e32 v12, v62, v81
	v_lshl_add_u64 v[20:21], s[94:95], 0, v[144:145]
	ds_write_b32 v18, v17 offset:8704
	v_cvt_pk_bf16_f32 v17, v17, s0
	ds_write_b32 v12, v16 offset:8704
	v_cvt_pk_bf16_f32 v12, v16, s0
	v_lshl_add_u64 v[28:29], v[20:21], 0, v[54:55]
	ds_write_b16 v103, v17 offset:26960
	ds_write_b16 v103, v12 offset:27104
	s_waitcnt lgkmcnt(0)
	s_barrier
	s_mov_b32 s5, 0x3e4ccccd
	ds_read_b128 v[12:15], v229 offset:25088
	ds_read_b128 v[16:19], v229 offset:25152
	ds_read_b128 v[28:31], v230 offset:8704
	s_waitcnt lgkmcnt(1)
	v_mfma_f32_16x16x32_bf16 v[20:23], v[180:183], v[12:15], 0
	v_mfma_f32_16x16x32_bf16 v[24:27], v[188:191], v[12:15], 0
	v_mfma_f32_16x16x32_bf16 v[20:23], v[184:187], v[16:19], v[20:23]
	v_mfma_f32_16x16x32_bf16 v[24:27], v[192:195], v[16:19], v[24:27]
	s_nop 7
	s_nop 3
	s_waitcnt lgkmcnt(0)
	v_add_f32_e32 v20, v20, v122
	v_add_f32_e32 v21, v21, v123
	v_add_f32_e32 v24, v24, v126
	v_add_f32_e32 v25, v25, v127
	v_mul_f32_e32 v20, 0xbfb8aa3b, v20
	v_mul_f32_e32 v21, 0xbfb8aa3b, v21
	v_mul_f32_e32 v24, 0xbfb8aa3b, v24
	v_mul_f32_e32 v25, 0xbfb8aa3b, v25
	v_exp_f32_e32 v20, v20
	v_exp_f32_e32 v21, v21
	v_exp_f32_e32 v24, v24
	v_exp_f32_e32 v25, v25
	v_add_f32_e32 v20, 1.0, v20
	v_add_f32_e32 v21, 1.0, v21
	v_add_f32_e32 v24, 1.0, v24
	v_add_f32_e32 v25, 1.0, v25
	v_rcp_f32_e32 v20, v20
	v_rcp_f32_e32 v21, v21
	v_rcp_f32_e32 v24, v24
	v_rcp_f32_e32 v25, v25
	v_pk_mul_f32 v[12:13], v[20:21], v[130:131]
	s_nop 0
	v_pk_add_f32 v[14:15], v[12:13], v[12:13]
	v_mul_f32_e32 v20, 0x3fb8aa3b, v12
	v_mul_f32_e32 v21, 0x3fb8aa3b, v13
	v_exp_f32_e32 v20, v20
	v_exp_f32_e32 v21, v21
	v_mul_f32_e32 v16, 0x3e800000, v14
	v_fma_f32 v17, v14, s5, 1.0
	v_mul_f32_e32 v18, 0x3eaaaaab, v14
	v_fma_f32 v16, v16, v17, 1.0
	v_mul_f32_e32 v17, 0.5, v14
	v_fma_f32 v18, v18, v16, 1.0
	v_fma_f32 v17, v17, v18, 1.0
	v_mul_f32_e64 v17, v17, -v14
	v_fma_f32 v16, -v20, v20, 1.0
	v_cmp_lt_f32_e32 vcc, s6, v14
	v_mul_f32_e32 v19, 0x3e800000, v15
	v_fma_f32 v12, v15, s5, 1.0
	v_cndmask_b32_e32 v16, v16, v17, vcc
	v_mul_f32_e32 v13, 0x3eaaaaab, v15
	v_fma_f32 v19, v19, v12, 1.0
	v_mul_f32_e32 v12, 0.5, v15
	v_fma_f32 v13, v13, v19, 1.0
	v_fma_f32 v12, v12, v13, 1.0
	v_mul_f32_e64 v12, v12, -v15
	v_fma_f32 v13, -v21, v21, 1.0
	v_cmp_lt_f32_e32 vcc, s6, v15
	v_sqrt_f32_e32 v16, v16
	s_nop 1
	v_cndmask_b32_e32 v17, v13, v12, vcc
	v_sqrt_f32_e32 v17, v17
	s_nop 0
	v_pk_mul_f32 v[24:25], v[24:25], v[16:17]
	s_nop 0
	v_pk_mul_f32 v[24:25], v[28:29], v[24:25]
	v_add_f32_e32 v22, v22, v124
	v_add_f32_e32 v23, v23, v125
	v_add_f32_e32 v26, v26, v128
	v_add_f32_e32 v27, v27, v129
	v_mul_f32_e32 v22, 0xbfb8aa3b, v22
	v_mul_f32_e32 v23, 0xbfb8aa3b, v23
	v_mul_f32_e32 v26, 0xbfb8aa3b, v26
	v_mul_f32_e32 v27, 0xbfb8aa3b, v27
	v_exp_f32_e32 v22, v22
	v_exp_f32_e32 v23, v23
	v_exp_f32_e32 v26, v26
	v_exp_f32_e32 v27, v27
	v_add_f32_e32 v22, 1.0, v22
	v_add_f32_e32 v23, 1.0, v23
	v_add_f32_e32 v26, 1.0, v26
	v_add_f32_e32 v27, 1.0, v27
	v_rcp_f32_e32 v22, v22
	v_rcp_f32_e32 v23, v23
	v_rcp_f32_e32 v26, v26
	v_rcp_f32_e32 v27, v27
	v_pk_mul_f32 v[12:13], v[22:23], v[132:133]
	s_nop 0
	v_pk_add_f32 v[14:15], v[12:13], v[12:13]
	v_mul_f32_e32 v22, 0x3fb8aa3b, v12
	v_mul_f32_e32 v23, 0x3fb8aa3b, v13
	v_exp_f32_e32 v22, v22
	v_exp_f32_e32 v23, v23
	v_mul_f32_e32 v16, 0x3e800000, v14
	v_fma_f32 v17, v14, s5, 1.0
	v_mul_f32_e32 v18, 0x3eaaaaab, v14
	v_fma_f32 v16, v16, v17, 1.0
	v_mul_f32_e32 v17, 0.5, v14
	v_fma_f32 v18, v18, v16, 1.0
	v_fma_f32 v17, v17, v18, 1.0
	v_mul_f32_e64 v17, v17, -v14
	v_fma_f32 v16, -v22, v22, 1.0
	v_cmp_lt_f32_e32 vcc, s6, v14
	v_mul_f32_e32 v19, 0x3e800000, v15
	v_fma_f32 v12, v15, s5, 1.0
	v_cndmask_b32_e32 v16, v16, v17, vcc
	v_mul_f32_e32 v13, 0x3eaaaaab, v15
	v_fma_f32 v19, v19, v12, 1.0
	v_mul_f32_e32 v12, 0.5, v15
	v_fma_f32 v13, v13, v19, 1.0
	v_fma_f32 v12, v12, v13, 1.0
	v_mul_f32_e64 v12, v12, -v15
	v_fma_f32 v13, -v23, v23, 1.0
	v_cmp_lt_f32_e32 vcc, s6, v15
	v_sqrt_f32_e32 v16, v16
	s_nop 1
	v_cndmask_b32_e32 v17, v13, v12, vcc
	v_sqrt_f32_e32 v17, v17
	s_nop 0
	v_pk_mul_f32 v[26:27], v[26:27], v[16:17]
	s_nop 0
	v_pk_mul_f32 v[26:27], v[30:31], v[26:27]
	ds_write_b128 v230, v[20:23] offset:34304
	ds_write_b128 v230, v[24:27] offset:50688
	ds_read_b128 v[12:15], v229 offset:27392
	ds_read_b128 v[16:19], v229 offset:27456
	ds_read_b128 v[28:31], v230 offset:12800
	s_waitcnt lgkmcnt(1)
; __device__ __forceinline__ float sigmoidf_(float x) { return __builtin_amdgcn_rcpf(1.0f + __expf(-x)); }
; template <bool FINAL>
; __device__ void phase_lru(const Params& p, int l, unsigned char* smem) {
;     ...
;         for (int et = 0; et < 4; ++et) {
;           f32x4 ar = {0.f, 0.f, 0.f, 0.f}, ai = {0.f, 0.f, 0.f, 0.f};
;           const u16* wr = p.WLRU + ((((size_t)(l * 2 + d) * 2 + 0) * 8 + nb) * 64 + et * 16 + l15) * 64 + g * 8;
;           const u16* wi = p.WLRU + ((((size_t)(l * 2 + d) * 2 + 1) * 8 + nb) * 64 + et * 16 + l15) * 64 + g * 8;
; #pragma unroll
;           for (int ks = 0; ks < 2; ++ks) {
;             ar = mfma16(*(const bf16x8*)(wr + ks * 32), uf[ks], ar);
;             ai = mfma16(*(const bf16x8*)(wi + ks * 32), uf[ks], ai);
;           }
;           const int e0 = et * 16 + 4 * g, ch0 = nb * 64 + e0;
;           const float4 ba4 = *(const float4*)(p.ba + (l * 2 + d) * 512 + ch0);
;           const float4 bx4 = *(const float4*)(p.bx + (l * 2 + d) * 512 + ch0);
;           const float4 sp4 = *(const float4*)(p.SP8 + (l * 2 + d) * 512 + ch0);
;           const float4 uu = *(const float4*)(u32 + t * 64 + e0);
;           const float* bap = (const float*)&ba4; const float* bxp = (const float*)&bx4;
;           const float* spp = (const float*)&sp4; const float* uup = (const float*)&uu;
;           f32x4 av, bv;
; #pragma unroll
;           for (int j = 0; j < 4; ++j) {
;             float r = sigmoidf_(ar[j] + bap[j]);
;             float ig = sigmoidf_(ai[j] + bxp[j]);
;             float la = spp[j] * r;
;             float av_ = __expf(la);
;             float t2 = 2.0f * la;
;             float ser = -t2 * (1.f + t2 * 0.5f * (1.f + t2 * (1.f / 3.f) * (1.f + t2 * 0.25f * (1.f + t2 * 0.2f))));
;             float om = (t2 > -0.25f) ? ser : (1.0f - av_ * av_);
;             av[j] = av_;
;             bv[j] = __builtin_amdgcn_sqrtf(om) * ig * uup[j];
;           }
;           *(f32x4*)(sa + t * 64 + e0) = av;
;           *(f32x4*)(sb + t * 64 + e0) = bv;
;         }
	v_mfma_f32_16x16x32_bf16 v[20:23], v[180:183], v[12:15], 0
	v_mfma_f32_16x16x32_bf16 v[24:27], v[188:191], v[12:15], 0
	v_mfma_f32_16x16x32_bf16 v[20:23], v[184:187], v[16:19], v[20:23]
	v_mfma_f32_16x16x32_bf16 v[24:27], v[192:195], v[16:19], v[24:27]
	s_nop 7
	s_nop 3
	s_waitcnt lgkmcnt(0)
	v_add_f32_e32 v20, v20, v122
	v_add_f32_e32 v21, v21, v123
	v_add_f32_e32 v24, v24, v126
	v_add_f32_e32 v25, v25, v127
	v_mul_f32_e32 v20, 0xbfb8aa3b, v20
	v_mul_f32_e32 v21, 0xbfb8aa3b, v21
	v_mul_f32_e32 v24, 0xbfb8aa3b, v24
	v_mul_f32_e32 v25, 0xbfb8aa3b, v25
	v_exp_f32_e32 v20, v20
	v_exp_f32_e32 v21, v21
	v_exp_f32_e32 v24, v24
	v_exp_f32_e32 v25, v25
	v_add_f32_e32 v20, 1.0, v20
	v_add_f32_e32 v21, 1.0, v21
	v_add_f32_e32 v24, 1.0, v24
	v_add_f32_e32 v25, 1.0, v25
	v_rcp_f32_e32 v20, v20
	v_rcp_f32_e32 v21, v21
	v_rcp_f32_e32 v24, v24
	v_rcp_f32_e32 v25, v25
	v_pk_mul_f32 v[12:13], v[20:21], v[130:131]
	s_nop 0
	v_pk_add_f32 v[14:15], v[12:13], v[12:13]
	v_mul_f32_e32 v20, 0x3fb8aa3b, v12
	v_mul_f32_e32 v21, 0x3fb8aa3b, v13
	v_exp_f32_e32 v20, v20
	v_exp_f32_e32 v21, v21
	v_mul_f32_e32 v16, 0x3e800000, v14
	v_fma_f32 v17, v14, s5, 1.0
	v_mul_f32_e32 v18, 0x3eaaaaab, v14
	v_fma_f32 v16, v16, v17, 1.0
	v_mul_f32_e32 v17, 0.5, v14
	v_fma_f32 v18, v18, v16, 1.0
	v_fma_f32 v17, v17, v18, 1.0
	v_mul_f32_e64 v17, v17, -v14
	v_fma_f32 v16, -v20, v20, 1.0
	v_cmp_lt_f32_e32 vcc, s6, v14
	v_mul_f32_e32 v19, 0x3e800000, v15
	v_fma_f32 v12, v15, s5, 1.0
	v_cndmask_b32_e32 v16, v16, v17, vcc
	v_mul_f32_e32 v13, 0x3eaaaaab, v15
	v_fma_f32 v19, v19, v12, 1.0
	v_mul_f32_e32 v12, 0.5, v15
	v_fma_f32 v13, v13, v19, 1.0
	v_fma_f32 v12, v12, v13, 1.0
	v_mul_f32_e64 v12, v12, -v15
	v_fma_f32 v13, -v21, v21, 1.0
	v_cmp_lt_f32_e32 vcc, s6, v15
	v_sqrt_f32_e32 v16, v16
	s_nop 1
	v_cndmask_b32_e32 v17, v13, v12, vcc
	v_sqrt_f32_e32 v17, v17
	s_nop 0
	v_pk_mul_f32 v[24:25], v[24:25], v[16:17]
	s_nop 0
	v_pk_mul_f32 v[24:25], v[28:29], v[24:25]
	v_add_f32_e32 v22, v22, v124
	v_add_f32_e32 v23, v23, v125
	v_add_f32_e32 v26, v26, v128
	v_add_f32_e32 v27, v27, v129
	v_mul_f32_e32 v22, 0xbfb8aa3b, v22
	v_mul_f32_e32 v23, 0xbfb8aa3b, v23
	v_mul_f32_e32 v26, 0xbfb8aa3b, v26
	v_mul_f32_e32 v27, 0xbfb8aa3b, v27
	v_exp_f32_e32 v22, v22
	v_exp_f32_e32 v23, v23
	v_exp_f32_e32 v26, v26
	v_exp_f32_e32 v27, v27
	v_add_f32_e32 v22, 1.0, v22
	v_add_f32_e32 v23, 1.0, v23
	v_add_f32_e32 v26, 1.0, v26
	v_add_f32_e32 v27, 1.0, v27
	v_rcp_f32_e32 v22, v22
	v_rcp_f32_e32 v23, v23
	v_rcp_f32_e32 v26, v26
	v_rcp_f32_e32 v27, v27
	v_pk_mul_f32 v[12:13], v[22:23], v[132:133]
	s_nop 0
	v_pk_add_f32 v[14:15], v[12:13], v[12:13]
	v_mul_f32_e32 v22, 0x3fb8aa3b, v12
	v_mul_f32_e32 v23, 0x3fb8aa3b, v13
	v_exp_f32_e32 v22, v22
	v_exp_f32_e32 v23, v23
	v_mul_f32_e32 v16, 0x3e800000, v14
	v_fma_f32 v17, v14, s5, 1.0
	v_mul_f32_e32 v18, 0x3eaaaaab, v14
	v_fma_f32 v16, v16, v17, 1.0
	v_mul_f32_e32 v17, 0.5, v14
	v_fma_f32 v18, v18, v16, 1.0
	v_fma_f32 v17, v17, v18, 1.0
	v_mul_f32_e64 v17, v17, -v14
	v_fma_f32 v16, -v22, v22, 1.0
	v_cmp_lt_f32_e32 vcc, s6, v14
	v_mul_f32_e32 v19, 0x3e800000, v15
	v_fma_f32 v12, v15, s5, 1.0
	v_cndmask_b32_e32 v16, v16, v17, vcc
	v_mul_f32_e32 v13, 0x3eaaaaab, v15
	v_fma_f32 v19, v19, v12, 1.0
	v_mul_f32_e32 v12, 0.5, v15
	v_fma_f32 v13, v13, v19, 1.0
	v_fma_f32 v12, v12, v13, 1.0
	v_mul_f32_e64 v12, v12, -v15
	v_fma_f32 v13, -v23, v23, 1.0
	v_cmp_lt_f32_e32 vcc, s6, v15
	v_sqrt_f32_e32 v16, v16
	s_nop 1
	v_cndmask_b32_e32 v17, v13, v12, vcc
	v_sqrt_f32_e32 v17, v17
	s_nop 0
	v_pk_mul_f32 v[26:27], v[26:27], v[16:17]
	s_nop 0
	v_pk_mul_f32 v[26:27], v[30:31], v[26:27]
	ds_write_b128 v230, v[20:23] offset:38400
	ds_write_b128 v230, v[24:27] offset:54784
	ds_read_b128 v[12:15], v229 offset:29696
	ds_read_b128 v[16:19], v229 offset:29760
	ds_read_b128 v[28:31], v230 offset:16896
	s_waitcnt lgkmcnt(1)
	v_mfma_f32_16x16x32_bf16 v[20:23], v[180:183], v[12:15], 0
	v_mfma_f32_16x16x32_bf16 v[24:27], v[188:191], v[12:15], 0
	v_mfma_f32_16x16x32_bf16 v[20:23], v[184:187], v[16:19], v[20:23]
	v_mfma_f32_16x16x32_bf16 v[24:27], v[192:195], v[16:19], v[24:27]
	s_nop 7
	s_nop 3
	s_waitcnt lgkmcnt(0)
	v_add_f32_e32 v20, v20, v122
	v_add_f32_e32 v21, v21, v123
	v_add_f32_e32 v24, v24, v126
	v_add_f32_e32 v25, v25, v127
	v_mul_f32_e32 v20, 0xbfb8aa3b, v20
	v_mul_f32_e32 v21, 0xbfb8aa3b, v21
	v_mul_f32_e32 v24, 0xbfb8aa3b, v24
	v_mul_f32_e32 v25, 0xbfb8aa3b, v25
	v_exp_f32_e32 v20, v20
	v_exp_f32_e32 v21, v21
	v_exp_f32_e32 v24, v24
	v_exp_f32_e32 v25, v25
	v_add_f32_e32 v20, 1.0, v20
	v_add_f32_e32 v21, 1.0, v21
	v_add_f32_e32 v24, 1.0, v24
	v_add_f32_e32 v25, 1.0, v25
	v_rcp_f32_e32 v20, v20
	v_rcp_f32_e32 v21, v21
	v_rcp_f32_e32 v24, v24
	v_rcp_f32_e32 v25, v25
	v_pk_mul_f32 v[12:13], v[20:21], v[130:131]
	s_nop 0
	v_pk_add_f32 v[14:15], v[12:13], v[12:13]
	v_mul_f32_e32 v20, 0x3fb8aa3b, v12
	v_mul_f32_e32 v21, 0x3fb8aa3b, v13
	v_exp_f32_e32 v20, v20
	v_exp_f32_e32 v21, v21
	v_mul_f32_e32 v16, 0x3e800000, v14
	v_fma_f32 v17, v14, s5, 1.0
	v_mul_f32_e32 v18, 0x3eaaaaab, v14
	v_fma_f32 v16, v16, v17, 1.0
	v_mul_f32_e32 v17, 0.5, v14
	v_fma_f32 v18, v18, v16, 1.0
	v_fma_f32 v17, v17, v18, 1.0
	v_mul_f32_e64 v17, v17, -v14
	v_fma_f32 v16, -v20, v20, 1.0
	v_cmp_lt_f32_e32 vcc, s6, v14
	v_mul_f32_e32 v19, 0x3e800000, v15
	v_fma_f32 v12, v15, s5, 1.0
	v_cndmask_b32_e32 v16, v16, v17, vcc
	v_mul_f32_e32 v13, 0x3eaaaaab, v15
	v_fma_f32 v19, v19, v12, 1.0
	v_mul_f32_e32 v12, 0.5, v15
	v_fma_f32 v13, v13, v19, 1.0
	v_fma_f32 v12, v12, v13, 1.0
	v_mul_f32_e64 v12, v12, -v15
	v_fma_f32 v13, -v21, v21, 1.0
	v_cmp_lt_f32_e32 vcc, s6, v15
	v_sqrt_f32_e32 v16, v16
	s_nop 1
	v_cndmask_b32_e32 v17, v13, v12, vcc
; __device__ __forceinline__ float sigmoidf_(float x) { return __builtin_amdgcn_rcpf(1.0f + __expf(-x)); }
; template <bool FINAL>
; __device__ void phase_lru(const Params& p, int l, unsigned char* smem) {
;     ...
;         for (int et = 0; et < 4; ++et) {
;           f32x4 ar = {0.f, 0.f, 0.f, 0.f}, ai = {0.f, 0.f, 0.f, 0.f};
;           const u16* wr = p.WLRU + ((((size_t)(l * 2 + d) * 2 + 0) * 8 + nb) * 64 + et * 16 + l15) * 64 + g * 8;
;           const u16* wi = p.WLRU + ((((size_t)(l * 2 + d) * 2 + 1) * 8 + nb) * 64 + et * 16 + l15) * 64 + g * 8;
; #pragma unroll
;           for (int ks = 0; ks < 2; ++ks) {
;             ar = mfma16(*(const bf16x8*)(wr + ks * 32), uf[ks], ar);
;             ai = mfma16(*(const bf16x8*)(wi + ks * 32), uf[ks], ai);
;           }
;           const int e0 = et * 16 + 4 * g, ch0 = nb * 64 + e0;
;           const float4 ba4 = *(const float4*)(p.ba + (l * 2 + d) * 512 + ch0);
;           const float4 bx4 = *(const float4*)(p.bx + (l * 2 + d) * 512 + ch0);
;           const float4 sp4 = *(const float4*)(p.SP8 + (l * 2 + d) * 512 + ch0);
;           const float4 uu = *(const float4*)(u32 + t * 64 + e0);
;           const float* bap = (const float*)&ba4; const float* bxp = (const float*)&bx4;
;           const float* spp = (const float*)&sp4; const float* uup = (const float*)&uu;
;           f32x4 av, bv;
; #pragma unroll
;           for (int j = 0; j < 4; ++j) {
;             float r = sigmoidf_(ar[j] + bap[j]);
;             float ig = sigmoidf_(ai[j] + bxp[j]);
;             float la = spp[j] * r;
;             float av_ = __expf(la);
;             float t2 = 2.0f * la;
;             float ser = -t2 * (1.f + t2 * 0.5f * (1.f + t2 * (1.f / 3.f) * (1.f + t2 * 0.25f * (1.f + t2 * 0.2f))));
;             float om = (t2 > -0.25f) ? ser : (1.0f - av_ * av_);
;             av[j] = av_;
;             bv[j] = __builtin_amdgcn_sqrtf(om) * ig * uup[j];
;           }
;           *(f32x4*)(sa + t * 64 + e0) = av;
;           *(f32x4*)(sb + t * 64 + e0) = bv;
;         }
;       }
;       __syncthreads();
	v_sqrt_f32_e32 v17, v17
	s_nop 0
	v_pk_mul_f32 v[24:25], v[24:25], v[16:17]
	s_nop 0
	v_pk_mul_f32 v[24:25], v[28:29], v[24:25]
	v_add_f32_e32 v22, v22, v124
	v_add_f32_e32 v23, v23, v125
	v_add_f32_e32 v26, v26, v128
	v_add_f32_e32 v27, v27, v129
	v_mul_f32_e32 v22, 0xbfb8aa3b, v22
	v_mul_f32_e32 v23, 0xbfb8aa3b, v23
	v_mul_f32_e32 v26, 0xbfb8aa3b, v26
	v_mul_f32_e32 v27, 0xbfb8aa3b, v27
	v_exp_f32_e32 v22, v22
	v_exp_f32_e32 v23, v23
	v_exp_f32_e32 v26, v26
	v_exp_f32_e32 v27, v27
	v_add_f32_e32 v22, 1.0, v22
	v_add_f32_e32 v23, 1.0, v23
	v_add_f32_e32 v26, 1.0, v26
	v_add_f32_e32 v27, 1.0, v27
	v_rcp_f32_e32 v22, v22
	v_rcp_f32_e32 v23, v23
	v_rcp_f32_e32 v26, v26
	v_rcp_f32_e32 v27, v27
	v_pk_mul_f32 v[12:13], v[22:23], v[132:133]
	s_nop 0
	v_pk_add_f32 v[14:15], v[12:13], v[12:13]
	v_mul_f32_e32 v22, 0x3fb8aa3b, v12
	v_mul_f32_e32 v23, 0x3fb8aa3b, v13
	v_exp_f32_e32 v22, v22
	v_exp_f32_e32 v23, v23
	v_mul_f32_e32 v16, 0x3e800000, v14
	v_fma_f32 v17, v14, s5, 1.0
	v_mul_f32_e32 v18, 0x3eaaaaab, v14
	v_fma_f32 v16, v16, v17, 1.0
	v_mul_f32_e32 v17, 0.5, v14
	v_fma_f32 v18, v18, v16, 1.0
	v_fma_f32 v17, v17, v18, 1.0
	v_mul_f32_e64 v17, v17, -v14
	v_fma_f32 v16, -v22, v22, 1.0
	v_cmp_lt_f32_e32 vcc, s6, v14
	v_mul_f32_e32 v19, 0x3e800000, v15
	v_fma_f32 v12, v15, s5, 1.0
	v_cndmask_b32_e32 v16, v16, v17, vcc
	v_mul_f32_e32 v13, 0x3eaaaaab, v15
	v_fma_f32 v19, v19, v12, 1.0
	v_mul_f32_e32 v12, 0.5, v15
	v_fma_f32 v13, v13, v19, 1.0
	v_fma_f32 v12, v12, v13, 1.0
	v_mul_f32_e64 v12, v12, -v15
	v_fma_f32 v13, -v23, v23, 1.0
	v_cmp_lt_f32_e32 vcc, s6, v15
	v_sqrt_f32_e32 v16, v16
	s_nop 1
	v_cndmask_b32_e32 v17, v13, v12, vcc
	v_sqrt_f32_e32 v17, v17
	s_nop 0
	v_pk_mul_f32 v[26:27], v[26:27], v[16:17]
	s_nop 0
	v_pk_mul_f32 v[26:27], v[30:31], v[26:27]
	ds_write_b128 v230, v[20:23] offset:42496
	ds_write_b128 v230, v[24:27] offset:58880
	ds_read_b128 v[12:15], v229 offset:32000
	ds_read_b128 v[16:19], v229 offset:32064
	ds_read_b128 v[28:31], v230 offset:20992
	s_waitcnt lgkmcnt(1)
	v_mfma_f32_16x16x32_bf16 v[20:23], v[180:183], v[12:15], 0
	v_mfma_f32_16x16x32_bf16 v[24:27], v[188:191], v[12:15], 0
	v_mfma_f32_16x16x32_bf16 v[20:23], v[184:187], v[16:19], v[20:23]
	v_mfma_f32_16x16x32_bf16 v[24:27], v[192:195], v[16:19], v[24:27]
	s_nop 7
	s_nop 3
	s_waitcnt lgkmcnt(0)
	v_add_f32_e32 v20, v20, v122
	v_add_f32_e32 v21, v21, v123
	v_add_f32_e32 v24, v24, v126
	v_add_f32_e32 v25, v25, v127
	v_mul_f32_e32 v20, 0xbfb8aa3b, v20
	v_mul_f32_e32 v21, 0xbfb8aa3b, v21
	v_mul_f32_e32 v24, 0xbfb8aa3b, v24
	v_mul_f32_e32 v25, 0xbfb8aa3b, v25
	v_exp_f32_e32 v20, v20
	v_exp_f32_e32 v21, v21
	v_exp_f32_e32 v24, v24
	v_exp_f32_e32 v25, v25
	v_add_f32_e32 v20, 1.0, v20
	v_add_f32_e32 v21, 1.0, v21
	v_add_f32_e32 v24, 1.0, v24
	v_add_f32_e32 v25, 1.0, v25
	v_rcp_f32_e32 v20, v20
	v_rcp_f32_e32 v21, v21
	v_rcp_f32_e32 v24, v24
	v_rcp_f32_e32 v25, v25
	v_pk_mul_f32 v[12:13], v[20:21], v[130:131]
	s_nop 0
	v_pk_add_f32 v[14:15], v[12:13], v[12:13]
	v_mul_f32_e32 v20, 0x3fb8aa3b, v12
	v_mul_f32_e32 v21, 0x3fb8aa3b, v13
	v_exp_f32_e32 v20, v20
	v_exp_f32_e32 v21, v21
	v_mul_f32_e32 v16, 0x3e800000, v14
	v_fma_f32 v17, v14, s5, 1.0
	v_mul_f32_e32 v18, 0x3eaaaaab, v14
	v_fma_f32 v16, v16, v17, 1.0
	v_mul_f32_e32 v17, 0.5, v14
	v_fma_f32 v18, v18, v16, 1.0
	v_fma_f32 v17, v17, v18, 1.0
	v_mul_f32_e64 v17, v17, -v14
	v_fma_f32 v16, -v20, v20, 1.0
	v_cmp_lt_f32_e32 vcc, s6, v14
	v_mul_f32_e32 v19, 0x3e800000, v15
	v_fma_f32 v12, v15, s5, 1.0
	v_cndmask_b32_e32 v16, v16, v17, vcc
	v_mul_f32_e32 v13, 0x3eaaaaab, v15
	v_fma_f32 v19, v19, v12, 1.0
	v_mul_f32_e32 v12, 0.5, v15
	v_fma_f32 v13, v13, v19, 1.0
	v_fma_f32 v12, v12, v13, 1.0
	v_mul_f32_e64 v12, v12, -v15
	v_fma_f32 v13, -v21, v21, 1.0
	v_cmp_lt_f32_e32 vcc, s6, v15
	v_sqrt_f32_e32 v16, v16
	s_nop 1
	v_cndmask_b32_e32 v17, v13, v12, vcc
	v_sqrt_f32_e32 v17, v17
	s_nop 0
	v_pk_mul_f32 v[24:25], v[24:25], v[16:17]
	s_nop 0
	v_pk_mul_f32 v[24:25], v[28:29], v[24:25]
	v_add_f32_e32 v22, v22, v124
	v_add_f32_e32 v23, v23, v125
	v_add_f32_e32 v26, v26, v128
	v_add_f32_e32 v27, v27, v129
	v_mul_f32_e32 v22, 0xbfb8aa3b, v22
	v_mul_f32_e32 v23, 0xbfb8aa3b, v23
	v_mul_f32_e32 v26, 0xbfb8aa3b, v26
	v_mul_f32_e32 v27, 0xbfb8aa3b, v27
	v_exp_f32_e32 v22, v22
	v_exp_f32_e32 v23, v23
	v_exp_f32_e32 v26, v26
	v_exp_f32_e32 v27, v27
	v_add_f32_e32 v22, 1.0, v22
	v_add_f32_e32 v23, 1.0, v23
	v_add_f32_e32 v26, 1.0, v26
	v_add_f32_e32 v27, 1.0, v27
	v_rcp_f32_e32 v22, v22
	v_rcp_f32_e32 v23, v23
	v_rcp_f32_e32 v26, v26
	v_rcp_f32_e32 v27, v27
	v_pk_mul_f32 v[12:13], v[22:23], v[132:133]
	s_nop 0
	v_pk_add_f32 v[14:15], v[12:13], v[12:13]
	v_mul_f32_e32 v22, 0x3fb8aa3b, v12
	v_mul_f32_e32 v23, 0x3fb8aa3b, v13
	v_exp_f32_e32 v22, v22
	v_exp_f32_e32 v23, v23
	v_mul_f32_e32 v16, 0x3e800000, v14
	v_fma_f32 v17, v14, s5, 1.0
	v_mul_f32_e32 v18, 0x3eaaaaab, v14
	v_fma_f32 v16, v16, v17, 1.0
	v_mul_f32_e32 v17, 0.5, v14
	v_fma_f32 v18, v18, v16, 1.0
	v_fma_f32 v17, v17, v18, 1.0
	v_mul_f32_e64 v17, v17, -v14
	v_fma_f32 v16, -v22, v22, 1.0
	v_cmp_lt_f32_e32 vcc, s6, v14
	v_mul_f32_e32 v19, 0x3e800000, v15
	v_fma_f32 v12, v15, s5, 1.0
	v_cndmask_b32_e32 v16, v16, v17, vcc
	v_mul_f32_e32 v13, 0x3eaaaaab, v15
	v_fma_f32 v19, v19, v12, 1.0
	v_mul_f32_e32 v12, 0.5, v15
	v_fma_f32 v13, v13, v19, 1.0
	v_fma_f32 v12, v12, v13, 1.0
	v_mul_f32_e64 v12, v12, -v15
	v_fma_f32 v13, -v23, v23, 1.0
	v_cmp_lt_f32_e32 vcc, s6, v15
	v_sqrt_f32_e32 v16, v16
	s_nop 1
	v_cndmask_b32_e32 v17, v13, v12, vcc
	v_sqrt_f32_e32 v17, v17
	s_nop 0
	v_pk_mul_f32 v[26:27], v[26:27], v[16:17]
	s_nop 0
	v_pk_mul_f32 v[26:27], v[30:31], v[26:27]
	ds_write_b128 v230, v[20:23] offset:46592
	ds_write_b128 v230, v[24:27] offset:62976
	s_waitcnt lgkmcnt(0)
	s_barrier
; template <bool FINAL>
; __device__ void phase_lru(const Params& p, int l, unsigned char* smem) {
;     ...
;         for (int et = 0; et < 4; ++et) {
;           f32x4 ar = {0.f, 0.f, 0.f, 0.f}, ai = {0.f, 0.f, 0.f, 0.f};
;           const u16* wr = p.WLRU + ((((size_t)(l * 2 + d) * 2 + 0) * 8 + nb) * 64 + et * 16 + l15) * 64 + g * 8;
;           const u16* wi = p.WLRU + ((((size_t)(l * 2 + d) * 2 + 1) * 8 + nb) * 64 + et * 16 + l15) * 64 + g * 8;
; #pragma unroll
;           for (int ks = 0; ks < 2; ++ks) {
;             ar = mfma16(*(const bf16x8*)(wr + ks * 32), uf[ks], ar);
;             ai = mfma16(*(const bf16x8*)(wi + ks * 32), uf[ks], ai);
;           }
;           const int e0 = et * 16 + 4 * g, ch0 = nb * 64 + e0;
;           const float4 ba4 = *(const float4*)(p.ba + (l * 2 + d) * 512 + ch0);
;           const float4 bx4 = *(const float4*)(p.bx + (l * 2 + d) * 512 + ch0);
;           const float4 sp4 = *(const float4*)(p.SP8 + (l * 2 + d) * 512 + ch0);
;           const float4 uu = *(const float4*)(u32 + t * 64 + e0);
;           const float* bap = (const float*)&ba4; const float* bxp = (const float*)&bx4;
;           const float* spp = (const float*)&sp4; const float* uup = (const float*)&uu;
;           f32x4 av, bv;
; #pragma unroll
;           for (int j = 0; j < 4; ++j) {
;             float r = sigmoidf_(ar[j] + bap[j]);
;             float ig = sigmoidf_(ai[j] + bxp[j]);
;     ...
;       {
;         float A = 1.f, B = 0.f;
;         if (d == 0) {
; #pragma unroll
;           for (int tt = 0; tt < 16; ++tt) { int t = qd * 16 + tt; float a = sa[t * 64 + e_], b = sb[t * 64 + e_]; B = a * B + b; A *= a; }
;         } else {
; #pragma unroll
;     ...
;         }
;         part[(0 * 4 + qd) * 64 + e_] = A;
;         part[(1 * 4 + qd) * 64 + e_] = B;
;       }
;       __syncthreads();
;       if (!FINAL) {
;         if (qd == 0) {
;           float A = 1.f, B = 0.f;
;           if (d == 0) {
; #pragma unroll
;             for (int q = 0; q < 4; ++q) { float aq = part[q * 64 + e_], bq = part[(4 + q) * 64 + e_]; B = aq * B + bq; A *= aq; }
;           } else {
; #pragma unroll
;             for (int q = 3; q >= 0; --q) { float aq = part[q * 64 + e_], bq = part[(4 + q) * 64 + e_]; B = aq * B + bq; A *= aq; }
;           }
;           const size_t cidx = ((size_t)ci * 2 + d) * 512 + nb * 64 + e_;
;           p.CA[cidx] = A; p.CB[cidx] = B;
;         }
	ds_read2st64_b32 v[12:13], v49 offset0:134 offset1:198
	ds_read2st64_b32 v[14:15], v82 offset0:134 offset1:198
	ds_read2st64_b32 v[16:17], v83 offset0:134 offset1:198
	s_waitcnt lgkmcnt(2)
	v_fmac_f32_e32 v13, 0, v12
	s_waitcnt lgkmcnt(1)
	v_mul_f32_e32 v18, v12, v14
	s_waitcnt lgkmcnt(0)
	v_mul_f32_e32 v20, v18, v16
	ds_read2st64_b32 v[18:19], v84 offset0:134 offset1:198
	v_fmac_f32_e32 v15, v14, v13
	v_fmac_f32_e32 v17, v16, v15
	v_lshlrev_b64 v[12:13], 2, v[50:51]
	v_lshl_add_u64 v[50:51], s[86:87], 0, v[12:13]
	s_waitcnt lgkmcnt(0)
	v_mul_f32_e32 v22, v20, v18
	ds_read2st64_b32 v[20:21], v85 offset0:134 offset1:198
	v_fmac_f32_e32 v19, v18, v17
	s_waitcnt lgkmcnt(0)
	v_mul_f32_e32 v24, v22, v20
	ds_read2st64_b32 v[22:23], v86 offset0:134 offset1:198
	v_fmac_f32_e32 v21, v20, v19
	s_waitcnt lgkmcnt(0)
	v_mul_f32_e32 v26, v24, v22
	ds_read2st64_b32 v[24:25], v87 offset0:134 offset1:198
	v_fmac_f32_e32 v23, v22, v21
	s_waitcnt lgkmcnt(0)
	v_mul_f32_e32 v28, v26, v24
	ds_read2st64_b32 v[26:27], v88 offset0:134 offset1:198
	v_fmac_f32_e32 v25, v24, v23
	s_waitcnt lgkmcnt(0)
	v_mul_f32_e32 v30, v28, v26
	ds_read2st64_b32 v[28:29], v89 offset0:134 offset1:198
	v_fmac_f32_e32 v27, v26, v25
	s_waitcnt lgkmcnt(0)
	v_mul_f32_e32 v32, v30, v28
	ds_read2st64_b32 v[30:31], v90 offset0:134 offset1:198
	v_fmac_f32_e32 v29, v28, v27
	s_waitcnt lgkmcnt(0)
	v_mul_f32_e32 v34, v32, v30
	ds_read2st64_b32 v[32:33], v91 offset0:134 offset1:198
	v_fmac_f32_e32 v31, v30, v29
	s_waitcnt lgkmcnt(0)
	v_mul_f32_e32 v52, v34, v32
	ds_read2st64_b32 v[34:35], v92 offset0:134 offset1:198
	v_fmac_f32_e32 v33, v32, v31
	s_waitcnt lgkmcnt(0)
	v_mul_f32_e32 v104, v52, v34
	ds_read2st64_b32 v[52:53], v93 offset0:134 offset1:198
	v_fmac_f32_e32 v35, v34, v33
	s_waitcnt lgkmcnt(0)
	v_mul_f32_e32 v106, v104, v52
	ds_read2st64_b32 v[104:105], v94 offset0:134 offset1:198
	v_fmac_f32_e32 v53, v52, v35
	s_waitcnt lgkmcnt(0)
	v_mul_f32_e32 v108, v106, v104
	ds_read2st64_b32 v[106:107], v95 offset0:134 offset1:198
	v_fmac_f32_e32 v105, v104, v53
	v_lshl_add_u64 v[52:53], s[88:89], 0, v[12:13]
	s_waitcnt lgkmcnt(0)
	v_mul_f32_e32 v110, v108, v106
	ds_read2st64_b32 v[108:109], v96 offset0:134 offset1:198
	v_fmac_f32_e32 v107, v106, v105
	s_waitcnt lgkmcnt(0)
	v_mul_f32_e32 v110, v110, v108
	v_fmac_f32_e32 v109, v108, v107
	ds_write_b32 v64, v110
	ds_write_b32 v65, v109 offset:1024
	s_waitcnt lgkmcnt(0)
	s_barrier
	s_and_saveexec_b64 s[42:43], s[40:41]
	s_cbranch_execz .LBB0_387
	ds_read2st64_b32 v[12:13], v64 offset1:1
	ds_read2st64_b32 v[14:15], v64 offset0:2 offset1:3
	s_waitcnt lgkmcnt(1)
	v_mul_f32_e32 v16, v12, v13
	s_waitcnt lgkmcnt(0)
	v_mul_f32_e32 v16, v16, v14
	v_mul_f32_e32 v18, v16, v15
	ds_read2st64_b32 v[16:17], v64 offset0:4 offset1:5
	s_waitcnt lgkmcnt(0)
	v_fma_f32 v12, 0, v12, v16
	v_fmac_f32_e32 v17, v13, v12
	ds_read2st64_b32 v[12:13], v64 offset0:6 offset1:7
	s_waitcnt lgkmcnt(0)
	v_fma_f32 v12, v14, v17, v12
	v_fmac_f32_e32 v13, v15, v12
	global_store_dword v[50:51], v18, off
	global_store_dword v[52:53], v13, off
.LBB0_387:
	s_or_b64 exec, exec, s[42:43]
	v_lshl_add_u64 v[20:21], s[50:51], 0, v[144:145]
	v_lshl_add_u64 v[28:29], v[20:21], 0, v[54:55]
	s_barrier
	s_mov_b32 s5, 0x3e4ccccd
	ds_read_b128 v[12:15], v229 offset:25088
	ds_read_b128 v[16:19], v229 offset:25152
	ds_read_b128 v[28:31], v230 offset:8704
	s_waitcnt lgkmcnt(1)
	v_mfma_f32_16x16x32_bf16 v[20:23], v[232:235], v[12:15], 0
	v_mfma_f32_16x16x32_bf16 v[24:27], v[240:243], v[12:15], 0
	v_mfma_f32_16x16x32_bf16 v[20:23], v[236:239], v[16:19], v[20:23]
	v_mfma_f32_16x16x32_bf16 v[24:27], v[244:247], v[16:19], v[24:27]
	s_nop 7
	s_nop 3
	s_waitcnt lgkmcnt(0)
	v_add_f32_e32 v20, v20, v134
	v_add_f32_e32 v21, v21, v135
	v_add_f32_e32 v24, v24, v138
	v_add_f32_e32 v25, v25, v139
	v_mul_f32_e32 v20, 0xbfb8aa3b, v20
	v_mul_f32_e32 v21, 0xbfb8aa3b, v21
	v_mul_f32_e32 v24, 0xbfb8aa3b, v24
	v_mul_f32_e32 v25, 0xbfb8aa3b, v25
	v_exp_f32_e32 v20, v20
	v_exp_f32_e32 v21, v21
	v_exp_f32_e32 v24, v24
	v_exp_f32_e32 v25, v25
	v_add_f32_e32 v20, 1.0, v20
	v_add_f32_e32 v21, 1.0, v21
	v_add_f32_e32 v24, 1.0, v24
	v_add_f32_e32 v25, 1.0, v25
	v_rcp_f32_e32 v20, v20
	v_rcp_f32_e32 v21, v21
	v_rcp_f32_e32 v24, v24
	v_rcp_f32_e32 v25, v25
	v_pk_mul_f32 v[12:13], v[20:21], v[150:151]
	s_nop 0
	v_pk_add_f32 v[14:15], v[12:13], v[12:13]
	v_mul_f32_e32 v20, 0x3fb8aa3b, v12
	v_mul_f32_e32 v21, 0x3fb8aa3b, v13
	v_exp_f32_e32 v20, v20
	v_exp_f32_e32 v21, v21
	v_mul_f32_e32 v16, 0x3e800000, v14
	v_fma_f32 v17, v14, s5, 1.0
	v_mul_f32_e32 v18, 0x3eaaaaab, v14
	v_fma_f32 v16, v16, v17, 1.0
	v_mul_f32_e32 v17, 0.5, v14
	v_fma_f32 v18, v18, v16, 1.0
	v_fma_f32 v17, v17, v18, 1.0
	v_mul_f32_e64 v17, v17, -v14
	v_fma_f32 v16, -v20, v20, 1.0
	v_cmp_lt_f32_e32 vcc, s6, v14
	v_mul_f32_e32 v19, 0x3e800000, v15
	v_fma_f32 v12, v15, s5, 1.0
	v_cndmask_b32_e32 v16, v16, v17, vcc
	v_mul_f32_e32 v13, 0x3eaaaaab, v15
	v_fma_f32 v19, v19, v12, 1.0
	v_mul_f32_e32 v12, 0.5, v15
	v_fma_f32 v13, v13, v19, 1.0
	v_fma_f32 v12, v12, v13, 1.0
	v_mul_f32_e64 v12, v12, -v15
	v_fma_f32 v13, -v21, v21, 1.0
	v_cmp_lt_f32_e32 vcc, s6, v15
	v_sqrt_f32_e32 v16, v16
	s_nop 1
	v_cndmask_b32_e32 v17, v13, v12, vcc
	v_sqrt_f32_e32 v17, v17
	s_nop 0
	v_pk_mul_f32 v[24:25], v[24:25], v[16:17]
	s_nop 0
	v_pk_mul_f32 v[24:25], v[28:29], v[24:25]
	v_add_f32_e32 v22, v22, v136
	v_add_f32_e32 v23, v23, v137
	v_add_f32_e32 v26, v26, v140
	v_add_f32_e32 v27, v27, v141
	v_mul_f32_e32 v22, 0xbfb8aa3b, v22
	v_mul_f32_e32 v23, 0xbfb8aa3b, v23
	v_mul_f32_e32 v26, 0xbfb8aa3b, v26
	v_mul_f32_e32 v27, 0xbfb8aa3b, v27
	v_exp_f32_e32 v22, v22
	v_exp_f32_e32 v23, v23
; __device__ __forceinline__ float sigmoidf_(float x) { return __builtin_amdgcn_rcpf(1.0f + __expf(-x)); }
; template <bool FINAL>
; __device__ void phase_lru(const Params& p, int l, unsigned char* smem) {
;     ...
;         for (int et = 0; et < 4; ++et) {
;           f32x4 ar = {0.f, 0.f, 0.f, 0.f}, ai = {0.f, 0.f, 0.f, 0.f};
;           const u16* wr = p.WLRU + ((((size_t)(l * 2 + d) * 2 + 0) * 8 + nb) * 64 + et * 16 + l15) * 64 + g * 8;
;           const u16* wi = p.WLRU + ((((size_t)(l * 2 + d) * 2 + 1) * 8 + nb) * 64 + et * 16 + l15) * 64 + g * 8;
; #pragma unroll
;           for (int ks = 0; ks < 2; ++ks) {
;             ar = mfma16(*(const bf16x8*)(wr + ks * 32), uf[ks], ar);
;             ai = mfma16(*(const bf16x8*)(wi + ks * 32), uf[ks], ai);
;           }
;           const int e0 = et * 16 + 4 * g, ch0 = nb * 64 + e0;
;           const float4 ba4 = *(const float4*)(p.ba + (l * 2 + d) * 512 + ch0);
;           const float4 bx4 = *(const float4*)(p.bx + (l * 2 + d) * 512 + ch0);
;           const float4 sp4 = *(const float4*)(p.SP8 + (l * 2 + d) * 512 + ch0);
;           const float4 uu = *(const float4*)(u32 + t * 64 + e0);
;           const float* bap = (const float*)&ba4; const float* bxp = (const float*)&bx4;
;           const float* spp = (const float*)&sp4; const float* uup = (const float*)&uu;
;           f32x4 av, bv;
; #pragma unroll
;           for (int j = 0; j < 4; ++j) {
;             float r = sigmoidf_(ar[j] + bap[j]);
;             float ig = sigmoidf_(ai[j] + bxp[j]);
;             float la = spp[j] * r;
;             float av_ = __expf(la);
;             float t2 = 2.0f * la;
;             float ser = -t2 * (1.f + t2 * 0.5f * (1.f + t2 * (1.f / 3.f) * (1.f + t2 * 0.25f * (1.f + t2 * 0.2f))));
;             float om = (t2 > -0.25f) ? ser : (1.0f - av_ * av_);
;             av[j] = av_;
;             bv[j] = __builtin_amdgcn_sqrtf(om) * ig * uup[j];
;           }
;           *(f32x4*)(sa + t * 64 + e0) = av;
;           *(f32x4*)(sb + t * 64 + e0) = bv;
;         }
	v_exp_f32_e32 v26, v26
	v_exp_f32_e32 v27, v27
	v_add_f32_e32 v22, 1.0, v22
	v_add_f32_e32 v23, 1.0, v23
	v_add_f32_e32 v26, 1.0, v26
	v_add_f32_e32 v27, 1.0, v27
	v_rcp_f32_e32 v22, v22
	v_rcp_f32_e32 v23, v23
	v_rcp_f32_e32 v26, v26
	v_rcp_f32_e32 v27, v27
	v_pk_mul_f32 v[12:13], v[22:23], v[152:153]
	s_nop 0
	v_pk_add_f32 v[14:15], v[12:13], v[12:13]
	v_mul_f32_e32 v22, 0x3fb8aa3b, v12
	v_mul_f32_e32 v23, 0x3fb8aa3b, v13
	v_exp_f32_e32 v22, v22
	v_exp_f32_e32 v23, v23
	v_mul_f32_e32 v16, 0x3e800000, v14
	v_fma_f32 v17, v14, s5, 1.0
	v_mul_f32_e32 v18, 0x3eaaaaab, v14
	v_fma_f32 v16, v16, v17, 1.0
	v_mul_f32_e32 v17, 0.5, v14
	v_fma_f32 v18, v18, v16, 1.0
	v_fma_f32 v17, v17, v18, 1.0
	v_mul_f32_e64 v17, v17, -v14
	v_fma_f32 v16, -v22, v22, 1.0
	v_cmp_lt_f32_e32 vcc, s6, v14
	v_mul_f32_e32 v19, 0x3e800000, v15
	v_fma_f32 v12, v15, s5, 1.0
	v_cndmask_b32_e32 v16, v16, v17, vcc
	v_mul_f32_e32 v13, 0x3eaaaaab, v15
	v_fma_f32 v19, v19, v12, 1.0
	v_mul_f32_e32 v12, 0.5, v15
	v_fma_f32 v13, v13, v19, 1.0
	v_fma_f32 v12, v12, v13, 1.0
	v_mul_f32_e64 v12, v12, -v15
	v_fma_f32 v13, -v23, v23, 1.0
	v_cmp_lt_f32_e32 vcc, s6, v15
	v_sqrt_f32_e32 v16, v16
	s_nop 1
	v_cndmask_b32_e32 v17, v13, v12, vcc
	v_sqrt_f32_e32 v17, v17
	s_nop 0
	v_pk_mul_f32 v[26:27], v[26:27], v[16:17]
	s_nop 0
	v_pk_mul_f32 v[26:27], v[30:31], v[26:27]
	ds_write_b128 v230, v[20:23] offset:34304
	ds_write_b128 v230, v[24:27] offset:50688
	ds_read_b128 v[12:15], v229 offset:27392
	ds_read_b128 v[16:19], v229 offset:27456
	ds_read_b128 v[28:31], v230 offset:12800
	s_waitcnt lgkmcnt(1)
	v_mfma_f32_16x16x32_bf16 v[20:23], v[232:235], v[12:15], 0
	v_mfma_f32_16x16x32_bf16 v[24:27], v[240:243], v[12:15], 0
	v_mfma_f32_16x16x32_bf16 v[20:23], v[236:239], v[16:19], v[20:23]
	v_mfma_f32_16x16x32_bf16 v[24:27], v[244:247], v[16:19], v[24:27]
	s_nop 7
	s_nop 3
	s_waitcnt lgkmcnt(0)
	v_add_f32_e32 v20, v20, v134
	v_add_f32_e32 v21, v21, v135
	v_add_f32_e32 v24, v24, v138
	v_add_f32_e32 v25, v25, v139
	v_mul_f32_e32 v20, 0xbfb8aa3b, v20
	v_mul_f32_e32 v21, 0xbfb8aa3b, v21
	v_mul_f32_e32 v24, 0xbfb8aa3b, v24
	v_mul_f32_e32 v25, 0xbfb8aa3b, v25
	v_exp_f32_e32 v20, v20
	v_exp_f32_e32 v21, v21
	v_exp_f32_e32 v24, v24
	v_exp_f32_e32 v25, v25
	v_add_f32_e32 v20, 1.0, v20
	v_add_f32_e32 v21, 1.0, v21
	v_add_f32_e32 v24, 1.0, v24
	v_add_f32_e32 v25, 1.0, v25
	v_rcp_f32_e32 v20, v20
	v_rcp_f32_e32 v21, v21
	v_rcp_f32_e32 v24, v24
	v_rcp_f32_e32 v25, v25
	v_pk_mul_f32 v[12:13], v[20:21], v[150:151]
	s_nop 0
	v_pk_add_f32 v[14:15], v[12:13], v[12:13]
	v_mul_f32_e32 v20, 0x3fb8aa3b, v12
	v_mul_f32_e32 v21, 0x3fb8aa3b, v13
	v_exp_f32_e32 v20, v20
	v_exp_f32_e32 v21, v21
	v_mul_f32_e32 v16, 0x3e800000, v14
	v_fma_f32 v17, v14, s5, 1.0
	v_mul_f32_e32 v18, 0x3eaaaaab, v14
	v_fma_f32 v16, v16, v17, 1.0
	v_mul_f32_e32 v17, 0.5, v14
	v_fma_f32 v18, v18, v16, 1.0
	v_fma_f32 v17, v17, v18, 1.0
	v_mul_f32_e64 v17, v17, -v14
	v_fma_f32 v16, -v20, v20, 1.0
	v_cmp_lt_f32_e32 vcc, s6, v14
	v_mul_f32_e32 v19, 0x3e800000, v15
	v_fma_f32 v12, v15, s5, 1.0
	v_cndmask_b32_e32 v16, v16, v17, vcc
	v_mul_f32_e32 v13, 0x3eaaaaab, v15
	v_fma_f32 v19, v19, v12, 1.0
	v_mul_f32_e32 v12, 0.5, v15
	v_fma_f32 v13, v13, v19, 1.0
	v_fma_f32 v12, v12, v13, 1.0
	v_mul_f32_e64 v12, v12, -v15
	v_fma_f32 v13, -v21, v21, 1.0
	v_cmp_lt_f32_e32 vcc, s6, v15
	v_sqrt_f32_e32 v16, v16
	s_nop 1
	v_cndmask_b32_e32 v17, v13, v12, vcc
	v_sqrt_f32_e32 v17, v17
	s_nop 0
	v_pk_mul_f32 v[24:25], v[24:25], v[16:17]
	s_nop 0
	v_pk_mul_f32 v[24:25], v[28:29], v[24:25]
	v_add_f32_e32 v22, v22, v136
	v_add_f32_e32 v23, v23, v137
	v_add_f32_e32 v26, v26, v140
	v_add_f32_e32 v27, v27, v141
	v_mul_f32_e32 v22, 0xbfb8aa3b, v22
	v_mul_f32_e32 v23, 0xbfb8aa3b, v23
	v_mul_f32_e32 v26, 0xbfb8aa3b, v26
	v_mul_f32_e32 v27, 0xbfb8aa3b, v27
	v_exp_f32_e32 v22, v22
	v_exp_f32_e32 v23, v23
	v_exp_f32_e32 v26, v26
	v_exp_f32_e32 v27, v27
	v_add_f32_e32 v22, 1.0, v22
	v_add_f32_e32 v23, 1.0, v23
	v_add_f32_e32 v26, 1.0, v26
	v_add_f32_e32 v27, 1.0, v27
	v_rcp_f32_e32 v22, v22
	v_rcp_f32_e32 v23, v23
	v_rcp_f32_e32 v26, v26
	v_rcp_f32_e32 v27, v27
	v_pk_mul_f32 v[12:13], v[22:23], v[152:153]
	s_nop 0
	v_pk_add_f32 v[14:15], v[12:13], v[12:13]
	v_mul_f32_e32 v22, 0x3fb8aa3b, v12
	v_mul_f32_e32 v23, 0x3fb8aa3b, v13
	v_exp_f32_e32 v22, v22
	v_exp_f32_e32 v23, v23
	v_mul_f32_e32 v16, 0x3e800000, v14
	v_fma_f32 v17, v14, s5, 1.0
	v_mul_f32_e32 v18, 0x3eaaaaab, v14
	v_fma_f32 v16, v16, v17, 1.0
	v_mul_f32_e32 v17, 0.5, v14
	v_fma_f32 v18, v18, v16, 1.0
	v_fma_f32 v17, v17, v18, 1.0
	v_mul_f32_e64 v17, v17, -v14
	v_fma_f32 v16, -v22, v22, 1.0
	v_cmp_lt_f32_e32 vcc, s6, v14
	v_mul_f32_e32 v19, 0x3e800000, v15
	v_fma_f32 v12, v15, s5, 1.0
	v_cndmask_b32_e32 v16, v16, v17, vcc
	v_mul_f32_e32 v13, 0x3eaaaaab, v15
	v_fma_f32 v19, v19, v12, 1.0
	v_mul_f32_e32 v12, 0.5, v15
	v_fma_f32 v13, v13, v19, 1.0
	v_fma_f32 v12, v12, v13, 1.0
	v_mul_f32_e64 v12, v12, -v15
	v_fma_f32 v13, -v23, v23, 1.0
	v_cmp_lt_f32_e32 vcc, s6, v15
	v_sqrt_f32_e32 v16, v16
	s_nop 1
	v_cndmask_b32_e32 v17, v13, v12, vcc
	v_sqrt_f32_e32 v17, v17
	s_nop 0
	v_pk_mul_f32 v[26:27], v[26:27], v[16:17]
	s_nop 0
	v_pk_mul_f32 v[26:27], v[30:31], v[26:27]
	ds_write_b128 v230, v[20:23] offset:38400
	ds_write_b128 v230, v[24:27] offset:54784
	ds_read_b128 v[12:15], v229 offset:29696
	ds_read_b128 v[16:19], v229 offset:29760
	ds_read_b128 v[28:31], v230 offset:16896
	s_waitcnt lgkmcnt(1)
	v_mfma_f32_16x16x32_bf16 v[20:23], v[232:235], v[12:15], 0
	v_mfma_f32_16x16x32_bf16 v[24:27], v[240:243], v[12:15], 0
	v_mfma_f32_16x16x32_bf16 v[20:23], v[236:239], v[16:19], v[20:23]
	v_mfma_f32_16x16x32_bf16 v[24:27], v[244:247], v[16:19], v[24:27]
	s_nop 7
	s_nop 3
	s_waitcnt lgkmcnt(0)
; __device__ __forceinline__ float sigmoidf_(float x) { return __builtin_amdgcn_rcpf(1.0f + __expf(-x)); }
; template <bool FINAL>
; __device__ void phase_lru(const Params& p, int l, unsigned char* smem) {
;     ...
;         for (int et = 0; et < 4; ++et) {
;           f32x4 ar = {0.f, 0.f, 0.f, 0.f}, ai = {0.f, 0.f, 0.f, 0.f};
;           const u16* wr = p.WLRU + ((((size_t)(l * 2 + d) * 2 + 0) * 8 + nb) * 64 + et * 16 + l15) * 64 + g * 8;
;           const u16* wi = p.WLRU + ((((size_t)(l * 2 + d) * 2 + 1) * 8 + nb) * 64 + et * 16 + l15) * 64 + g * 8;
; #pragma unroll
;           for (int ks = 0; ks < 2; ++ks) {
;             ar = mfma16(*(const bf16x8*)(wr + ks * 32), uf[ks], ar);
;             ai = mfma16(*(const bf16x8*)(wi + ks * 32), uf[ks], ai);
;           }
;           const int e0 = et * 16 + 4 * g, ch0 = nb * 64 + e0;
;           const float4 ba4 = *(const float4*)(p.ba + (l * 2 + d) * 512 + ch0);
;           const float4 bx4 = *(const float4*)(p.bx + (l * 2 + d) * 512 + ch0);
;           const float4 sp4 = *(const float4*)(p.SP8 + (l * 2 + d) * 512 + ch0);
;           const float4 uu = *(const float4*)(u32 + t * 64 + e0);
;           const float* bap = (const float*)&ba4; const float* bxp = (const float*)&bx4;
;           const float* spp = (const float*)&sp4; const float* uup = (const float*)&uu;
;           f32x4 av, bv;
; #pragma unroll
;           for (int j = 0; j < 4; ++j) {
;             float r = sigmoidf_(ar[j] + bap[j]);
;             float ig = sigmoidf_(ai[j] + bxp[j]);
;             float la = spp[j] * r;
;             float av_ = __expf(la);
;             float t2 = 2.0f * la;
;             float ser = -t2 * (1.f + t2 * 0.5f * (1.f + t2 * (1.f / 3.f) * (1.f + t2 * 0.25f * (1.f + t2 * 0.2f))));
;             float om = (t2 > -0.25f) ? ser : (1.0f - av_ * av_);
;             av[j] = av_;
;             bv[j] = __builtin_amdgcn_sqrtf(om) * ig * uup[j];
;           }
;           *(f32x4*)(sa + t * 64 + e0) = av;
;           *(f32x4*)(sb + t * 64 + e0) = bv;
;         }
	v_add_f32_e32 v20, v20, v134
	v_add_f32_e32 v21, v21, v135
	v_add_f32_e32 v24, v24, v138
	v_add_f32_e32 v25, v25, v139
	v_mul_f32_e32 v20, 0xbfb8aa3b, v20
	v_mul_f32_e32 v21, 0xbfb8aa3b, v21
	v_mul_f32_e32 v24, 0xbfb8aa3b, v24
	v_mul_f32_e32 v25, 0xbfb8aa3b, v25
	v_exp_f32_e32 v20, v20
	v_exp_f32_e32 v21, v21
	v_exp_f32_e32 v24, v24
	v_exp_f32_e32 v25, v25
	v_add_f32_e32 v20, 1.0, v20
	v_add_f32_e32 v21, 1.0, v21
	v_add_f32_e32 v24, 1.0, v24
	v_add_f32_e32 v25, 1.0, v25
	v_rcp_f32_e32 v20, v20
	v_rcp_f32_e32 v21, v21
	v_rcp_f32_e32 v24, v24
	v_rcp_f32_e32 v25, v25
	v_pk_mul_f32 v[12:13], v[20:21], v[150:151]
	s_nop 0
	v_pk_add_f32 v[14:15], v[12:13], v[12:13]
	v_mul_f32_e32 v20, 0x3fb8aa3b, v12
	v_mul_f32_e32 v21, 0x3fb8aa3b, v13
	v_exp_f32_e32 v20, v20
	v_exp_f32_e32 v21, v21
	v_mul_f32_e32 v16, 0x3e800000, v14
	v_fma_f32 v17, v14, s5, 1.0
	v_mul_f32_e32 v18, 0x3eaaaaab, v14
	v_fma_f32 v16, v16, v17, 1.0
	v_mul_f32_e32 v17, 0.5, v14
	v_fma_f32 v18, v18, v16, 1.0
	v_fma_f32 v17, v17, v18, 1.0
	v_mul_f32_e64 v17, v17, -v14
	v_fma_f32 v16, -v20, v20, 1.0
	v_cmp_lt_f32_e32 vcc, s6, v14
	v_mul_f32_e32 v19, 0x3e800000, v15
	v_fma_f32 v12, v15, s5, 1.0
	v_cndmask_b32_e32 v16, v16, v17, vcc
	v_mul_f32_e32 v13, 0x3eaaaaab, v15
	v_fma_f32 v19, v19, v12, 1.0
	v_mul_f32_e32 v12, 0.5, v15
	v_fma_f32 v13, v13, v19, 1.0
	v_fma_f32 v12, v12, v13, 1.0
	v_mul_f32_e64 v12, v12, -v15
	v_fma_f32 v13, -v21, v21, 1.0
	v_cmp_lt_f32_e32 vcc, s6, v15
	v_sqrt_f32_e32 v16, v16
	s_nop 1
	v_cndmask_b32_e32 v17, v13, v12, vcc
	v_sqrt_f32_e32 v17, v17
	s_nop 0
	v_pk_mul_f32 v[24:25], v[24:25], v[16:17]
	s_nop 0
	v_pk_mul_f32 v[24:25], v[28:29], v[24:25]
	v_add_f32_e32 v22, v22, v136
	v_add_f32_e32 v23, v23, v137
	v_add_f32_e32 v26, v26, v140
	v_add_f32_e32 v27, v27, v141
	v_mul_f32_e32 v22, 0xbfb8aa3b, v22
	v_mul_f32_e32 v23, 0xbfb8aa3b, v23
	v_mul_f32_e32 v26, 0xbfb8aa3b, v26
	v_mul_f32_e32 v27, 0xbfb8aa3b, v27
	v_exp_f32_e32 v22, v22
	v_exp_f32_e32 v23, v23
	v_exp_f32_e32 v26, v26
	v_exp_f32_e32 v27, v27
	v_add_f32_e32 v22, 1.0, v22
	v_add_f32_e32 v23, 1.0, v23
	v_add_f32_e32 v26, 1.0, v26
	v_add_f32_e32 v27, 1.0, v27
	v_rcp_f32_e32 v22, v22
	v_rcp_f32_e32 v23, v23
	v_rcp_f32_e32 v26, v26
	v_rcp_f32_e32 v27, v27
	v_pk_mul_f32 v[12:13], v[22:23], v[152:153]
	s_nop 0
	v_pk_add_f32 v[14:15], v[12:13], v[12:13]
	v_mul_f32_e32 v22, 0x3fb8aa3b, v12
	v_mul_f32_e32 v23, 0x3fb8aa3b, v13
	v_exp_f32_e32 v22, v22
	v_exp_f32_e32 v23, v23
	v_mul_f32_e32 v16, 0x3e800000, v14
	v_fma_f32 v17, v14, s5, 1.0
	v_mul_f32_e32 v18, 0x3eaaaaab, v14
	v_fma_f32 v16, v16, v17, 1.0
	v_mul_f32_e32 v17, 0.5, v14
	v_fma_f32 v18, v18, v16, 1.0
	v_fma_f32 v17, v17, v18, 1.0
	v_mul_f32_e64 v17, v17, -v14
	v_fma_f32 v16, -v22, v22, 1.0
	v_cmp_lt_f32_e32 vcc, s6, v14
	v_mul_f32_e32 v19, 0x3e800000, v15
	v_fma_f32 v12, v15, s5, 1.0
	v_cndmask_b32_e32 v16, v16, v17, vcc
	v_mul_f32_e32 v13, 0x3eaaaaab, v15
	v_fma_f32 v19, v19, v12, 1.0
	v_mul_f32_e32 v12, 0.5, v15
	v_fma_f32 v13, v13, v19, 1.0
	v_fma_f32 v12, v12, v13, 1.0
	v_mul_f32_e64 v12, v12, -v15
	v_fma_f32 v13, -v23, v23, 1.0
	v_cmp_lt_f32_e32 vcc, s6, v15
	v_sqrt_f32_e32 v16, v16
	s_nop 1
	v_cndmask_b32_e32 v17, v13, v12, vcc
	v_sqrt_f32_e32 v17, v17
	s_nop 0
	v_pk_mul_f32 v[26:27], v[26:27], v[16:17]
	s_nop 0
	v_pk_mul_f32 v[26:27], v[30:31], v[26:27]
	ds_write_b128 v230, v[20:23] offset:42496
	ds_write_b128 v230, v[24:27] offset:58880
	ds_read_b128 v[12:15], v229 offset:32000
	ds_read_b128 v[16:19], v229 offset:32064
	ds_read_b128 v[28:31], v230 offset:20992
	s_waitcnt lgkmcnt(1)
	v_mfma_f32_16x16x32_bf16 v[20:23], v[232:235], v[12:15], 0
	v_mfma_f32_16x16x32_bf16 v[24:27], v[240:243], v[12:15], 0
	v_mfma_f32_16x16x32_bf16 v[20:23], v[236:239], v[16:19], v[20:23]
	v_mfma_f32_16x16x32_bf16 v[24:27], v[244:247], v[16:19], v[24:27]
	s_nop 7
	s_nop 3
	s_waitcnt lgkmcnt(0)
; template <bool FINAL>
; __device__ void phase_lru(const Params& p, int l, unsigned char* smem) {
;     ...
;         for (int et = 0; et < 4; ++et) {
;           f32x4 ar = {0.f, 0.f, 0.f, 0.f}, ai = {0.f, 0.f, 0.f, 0.f};
;           const u16* wr = p.WLRU + ((((size_t)(l * 2 + d) * 2 + 0) * 8 + nb) * 64 + et * 16 + l15) * 64 + g * 8;
;           const u16* wi = p.WLRU + ((((size_t)(l * 2 + d) * 2 + 1) * 8 + nb) * 64 + et * 16 + l15) * 64 + g * 8;
; #pragma unroll
;           for (int ks = 0; ks < 2; ++ks) {
;             ar = mfma16(*(const bf16x8*)(wr + ks * 32), uf[ks], ar);
;             ai = mfma16(*(const bf16x8*)(wi + ks * 32), uf[ks], ai);
;           }
;           const int e0 = et * 16 + 4 * g, ch0 = nb * 64 + e0;
;           const float4 ba4 = *(const float4*)(p.ba + (l * 2 + d) * 512 + ch0);
;           const float4 bx4 = *(const float4*)(p.bx + (l * 2 + d) * 512 + ch0);
;           const float4 sp4 = *(const float4*)(p.SP8 + (l * 2 + d) * 512 + ch0);
;           const float4 uu = *(const float4*)(u32 + t * 64 + e0);
;           const float* bap = (const float*)&ba4; const float* bxp = (const float*)&bx4;
;           const float* spp = (const float*)&sp4; const float* uup = (const float*)&uu;
;           f32x4 av, bv;
; #pragma unroll
;           for (int j = 0; j < 4; ++j) {
;             float r = sigmoidf_(ar[j] + bap[j]);
;             float ig = sigmoidf_(ai[j] + bxp[j]);
;             float la = spp[j] * r;
;             float av_ = __expf(la);
;             float t2 = 2.0f * la;
;             float ser = -t2 * (1.f + t2 * 0.5f * (1.f + t2 * (1.f / 3.f) * (1.f + t2 * 0.25f * (1.f + t2 * 0.2f))));
;             float om = (t2 > -0.25f) ? ser : (1.0f - av_ * av_);
;             av[j] = av_;
;             bv[j] = __builtin_amdgcn_sqrtf(om) * ig * uup[j];
;           }
;           *(f32x4*)(sa + t * 64 + e0) = av;
;           *(f32x4*)(sb + t * 64 + e0) = bv;
;         }
;       }
;       __syncthreads();
;       {
;         float A = 1.f, B = 0.f;
;         if (d == 0) {
; #pragma unroll
;           for (int tt = 0; tt < 16; ++tt) { int t = qd * 16 + tt; float a = sa[t * 64 + e_], b = sb[t * 64 + e_]; B = a * B + b; A *= a; }
;         } else {
; #pragma unroll
;     ...
;         }
;         part[(0 * 4 + qd) * 64 + e_] = A;
;         part[(1 * 4 + qd) * 64 + e_] = B;
;       }
;       __syncthreads();
;       if (!FINAL) {
;         if (qd == 0) {
	v_add_f32_e32 v20, v20, v134
	v_add_f32_e32 v21, v21, v135
	v_add_f32_e32 v24, v24, v138
	v_add_f32_e32 v25, v25, v139
	v_mul_f32_e32 v20, 0xbfb8aa3b, v20
	v_mul_f32_e32 v21, 0xbfb8aa3b, v21
	v_mul_f32_e32 v24, 0xbfb8aa3b, v24
	v_mul_f32_e32 v25, 0xbfb8aa3b, v25
	v_exp_f32_e32 v20, v20
	v_exp_f32_e32 v21, v21
	v_exp_f32_e32 v24, v24
	v_exp_f32_e32 v25, v25
	v_add_f32_e32 v20, 1.0, v20
	v_add_f32_e32 v21, 1.0, v21
	v_add_f32_e32 v24, 1.0, v24
	v_add_f32_e32 v25, 1.0, v25
	v_rcp_f32_e32 v20, v20
	v_rcp_f32_e32 v21, v21
	v_rcp_f32_e32 v24, v24
	v_rcp_f32_e32 v25, v25
	v_pk_mul_f32 v[12:13], v[20:21], v[150:151]
	s_nop 0
	v_pk_add_f32 v[14:15], v[12:13], v[12:13]
	v_mul_f32_e32 v20, 0x3fb8aa3b, v12
	v_mul_f32_e32 v21, 0x3fb8aa3b, v13
	v_exp_f32_e32 v20, v20
	v_exp_f32_e32 v21, v21
	v_mul_f32_e32 v16, 0x3e800000, v14
	v_fma_f32 v17, v14, s5, 1.0
	v_mul_f32_e32 v18, 0x3eaaaaab, v14
	v_fma_f32 v16, v16, v17, 1.0
	v_mul_f32_e32 v17, 0.5, v14
	v_fma_f32 v18, v18, v16, 1.0
	v_fma_f32 v17, v17, v18, 1.0
	v_mul_f32_e64 v17, v17, -v14
	v_fma_f32 v16, -v20, v20, 1.0
	v_cmp_lt_f32_e32 vcc, s6, v14
	v_mul_f32_e32 v19, 0x3e800000, v15
	v_fma_f32 v12, v15, s5, 1.0
	v_cndmask_b32_e32 v16, v16, v17, vcc
	v_mul_f32_e32 v13, 0x3eaaaaab, v15
	v_fma_f32 v19, v19, v12, 1.0
	v_mul_f32_e32 v12, 0.5, v15
	v_fma_f32 v13, v13, v19, 1.0
	v_fma_f32 v12, v12, v13, 1.0
	v_mul_f32_e64 v12, v12, -v15
	v_fma_f32 v13, -v21, v21, 1.0
	v_cmp_lt_f32_e32 vcc, s6, v15
	v_sqrt_f32_e32 v16, v16
	s_nop 1
	v_cndmask_b32_e32 v17, v13, v12, vcc
	v_sqrt_f32_e32 v17, v17
	s_nop 0
	v_pk_mul_f32 v[24:25], v[24:25], v[16:17]
	s_nop 0
	v_pk_mul_f32 v[24:25], v[28:29], v[24:25]
	v_add_f32_e32 v22, v22, v136
	v_add_f32_e32 v23, v23, v137
	v_add_f32_e32 v26, v26, v140
	v_add_f32_e32 v27, v27, v141
	v_mul_f32_e32 v22, 0xbfb8aa3b, v22
	v_mul_f32_e32 v23, 0xbfb8aa3b, v23
	v_mul_f32_e32 v26, 0xbfb8aa3b, v26
	v_mul_f32_e32 v27, 0xbfb8aa3b, v27
	v_exp_f32_e32 v22, v22
	v_exp_f32_e32 v23, v23
	v_exp_f32_e32 v26, v26
	v_exp_f32_e32 v27, v27
	v_add_f32_e32 v22, 1.0, v22
	v_add_f32_e32 v23, 1.0, v23
	v_add_f32_e32 v26, 1.0, v26
	v_add_f32_e32 v27, 1.0, v27
	v_rcp_f32_e32 v22, v22
	v_rcp_f32_e32 v23, v23
	v_rcp_f32_e32 v26, v26
	v_rcp_f32_e32 v27, v27
	v_pk_mul_f32 v[12:13], v[22:23], v[152:153]
	s_nop 0
	v_pk_add_f32 v[14:15], v[12:13], v[12:13]
	v_mul_f32_e32 v22, 0x3fb8aa3b, v12
	v_mul_f32_e32 v23, 0x3fb8aa3b, v13
	v_exp_f32_e32 v22, v22
	v_exp_f32_e32 v23, v23
	v_mul_f32_e32 v16, 0x3e800000, v14
	v_fma_f32 v17, v14, s5, 1.0
	v_mul_f32_e32 v18, 0x3eaaaaab, v14
	v_fma_f32 v16, v16, v17, 1.0
	v_mul_f32_e32 v17, 0.5, v14
	v_fma_f32 v18, v18, v16, 1.0
	v_fma_f32 v17, v17, v18, 1.0
	v_mul_f32_e64 v17, v17, -v14
	v_fma_f32 v16, -v22, v22, 1.0
	v_cmp_lt_f32_e32 vcc, s6, v14
	v_mul_f32_e32 v19, 0x3e800000, v15
	v_fma_f32 v12, v15, s5, 1.0
	v_cndmask_b32_e32 v16, v16, v17, vcc
	v_mul_f32_e32 v13, 0x3eaaaaab, v15
	v_fma_f32 v19, v19, v12, 1.0
	v_mul_f32_e32 v12, 0.5, v15
	v_fma_f32 v13, v13, v19, 1.0
	v_fma_f32 v12, v12, v13, 1.0
	v_mul_f32_e64 v12, v12, -v15
	v_fma_f32 v13, -v23, v23, 1.0
	v_cmp_lt_f32_e32 vcc, s6, v15
	v_sqrt_f32_e32 v16, v16
	s_nop 1
	v_cndmask_b32_e32 v17, v13, v12, vcc
	v_sqrt_f32_e32 v17, v17
	s_nop 0
	v_pk_mul_f32 v[26:27], v[26:27], v[16:17]
	s_nop 0
	v_pk_mul_f32 v[26:27], v[30:31], v[26:27]
	ds_write_b128 v230, v[20:23] offset:46592
	ds_write_b128 v230, v[24:27] offset:62976
	s_waitcnt lgkmcnt(0)
	s_barrier
	ds_read2st64_b32 v[12:13], v96 offset0:134 offset1:198
	ds_read2st64_b32 v[14:15], v95 offset0:134 offset1:198
	ds_read2st64_b32 v[16:17], v94 offset0:134 offset1:198
	ds_read2st64_b32 v[104:105], v83 offset0:134 offset1:198
	ds_read2st64_b32 v[106:107], v82 offset0:134 offset1:198
	s_waitcnt lgkmcnt(4)
	v_fmac_f32_e32 v13, 0, v12
	s_waitcnt lgkmcnt(3)
	v_mul_f32_e32 v18, v12, v14
	s_waitcnt lgkmcnt(2)
	v_mul_f32_e32 v20, v18, v16
	ds_read2st64_b32 v[18:19], v93 offset0:134 offset1:198
	v_fmac_f32_e32 v15, v14, v13
	v_fmac_f32_e32 v17, v16, v15
	ds_read2st64_b32 v[108:109], v49 offset0:134 offset1:198
	s_waitcnt lgkmcnt(1)
	v_mul_f32_e32 v22, v20, v18
	ds_read2st64_b32 v[20:21], v92 offset0:134 offset1:198
	v_fmac_f32_e32 v19, v18, v17
	s_waitcnt lgkmcnt(0)
	v_mul_f32_e32 v24, v22, v20
	ds_read2st64_b32 v[22:23], v91 offset0:134 offset1:198
	v_fmac_f32_e32 v21, v20, v19
	s_waitcnt lgkmcnt(0)
	v_mul_f32_e32 v26, v24, v22
	ds_read2st64_b32 v[24:25], v90 offset0:134 offset1:198
	v_fmac_f32_e32 v23, v22, v21
	s_waitcnt lgkmcnt(0)
	v_mul_f32_e32 v28, v26, v24
	ds_read2st64_b32 v[26:27], v89 offset0:134 offset1:198
	v_fmac_f32_e32 v25, v24, v23
	s_waitcnt lgkmcnt(0)
	v_mul_f32_e32 v30, v28, v26
	ds_read2st64_b32 v[28:29], v88 offset0:134 offset1:198
	v_fmac_f32_e32 v27, v26, v25
	s_waitcnt lgkmcnt(0)
	v_mul_f32_e32 v32, v30, v28
	ds_read2st64_b32 v[30:31], v87 offset0:134 offset1:198
	v_fmac_f32_e32 v29, v28, v27
	s_waitcnt lgkmcnt(0)
	v_mul_f32_e32 v34, v32, v30
	ds_read2st64_b32 v[32:33], v86 offset0:134 offset1:198
	v_fmac_f32_e32 v31, v30, v29
	s_waitcnt lgkmcnt(0)
	v_mul_f32_e32 v54, v34, v32
	ds_read2st64_b32 v[34:35], v85 offset0:134 offset1:198
	v_fmac_f32_e32 v33, v32, v31
	s_waitcnt lgkmcnt(0)
	v_mul_f32_e32 v56, v54, v34
	ds_read2st64_b32 v[54:55], v84 offset0:134 offset1:198
	v_fmac_f32_e32 v35, v34, v33
	s_waitcnt lgkmcnt(0)
	v_mul_f32_e32 v56, v56, v54
	v_mul_f32_e32 v56, v56, v104
	v_fmac_f32_e32 v55, v54, v35
	v_mul_f32_e32 v56, v56, v106
	v_fmac_f32_e32 v105, v104, v55
	v_mul_f32_e32 v56, v56, v108
	v_fmac_f32_e32 v107, v106, v105
	v_fmac_f32_e32 v109, v108, v107
	ds_write_b32 v64, v56
	ds_write_b32 v65, v109 offset:1024
	s_waitcnt lgkmcnt(0)
	s_barrier
	s_and_saveexec_b64 s[42:43], s[40:41]
	s_cbranch_execz .LBB0_374
	ds_read2st64_b32 v[12:13], v64 offset0:2 offset1:3
	ds_read2st64_b32 v[14:15], v64 offset1:1
	ds_read_b32 v17, v97
	s_waitcnt lgkmcnt(2)
	v_mul_f32_e32 v16, v13, v12
	s_waitcnt lgkmcnt(1)
	v_mul_f32_e32 v16, v16, v15
	s_waitcnt lgkmcnt(0)
	v_fmac_f32_e32 v17, 0, v13
	ds_read_b32 v13, v98
	v_mul_f32_e32 v16, v16, v14
	s_waitcnt lgkmcnt(0)
	v_fmac_f32_e32 v13, v12, v17
	ds_read_b32 v12, v99
	s_waitcnt lgkmcnt(0)
	v_fmac_f32_e32 v12, v15, v13
	ds_read_b32 v13, v100
	s_waitcnt lgkmcnt(0)
	v_fmac_f32_e32 v13, v14, v12
	global_store_dword v[50:51], v16, off offset:2048
	global_store_dword v[52:53], v13, off offset:2048
	s_branch .LBB0_374
